# ATT QK^T ds_read prefetch pipelining; skip redundant vmcnt waits in first K-tile after epilogue (G_in,G_up); hoist G_up epilogue rstd loads
# speedup vs baseline: 1.0024x; 1.0024x over previous
;     __host__ __device__ bool next(int i, Unit& u) const {
;         const int rnd = nseg == 1 ? i : (i >> 1); u.seg = nseg == 1 ? 0 : (i & 1);
;         const long L = (long)rnd * G + c; if (L >= nwg) return false;
;         int wgid = (int)L; { const int q = nwg / NXCD, r = nwg % NXCD, xcd = wgid % NXCD, off = wgid / NXCD; wgid = (xcd < r ? xcd * (q + 1) : r * (q + 1) + (xcd - r) * q) + off; }
;         const int nig = WGM * nN, gid = wgid / nig, fm = gid * WGM, gsz = (nM - fm) < WGM ? (nM - fm) : WGM;
;         u.pm = fm + ((wgid % nig) % gsz); u.pn = (wgid % nig) / gsz; return true;
; template <class Epi, class Sched, bool ALIGN_EPI = false, bool SP2 = false, bool SLIVER = false>
; __device__ __forceinline__ void gemm_phase(PG8_LAS unsigned char* lds, const Gemm g, const Sched& S, const Epi& E) {
;     ...
;         const bool has_next = S.next(ui + 1, nxt);
.LBB0_150:
	s_add_i32 s45, s45, 1
	s_cmp_gt_u32 s45, 1
	s_cselect_b32 s101, -2, 0x7ffffff0
	s_mul_i32 s12, s45, s42
	s_mul_hi_u32 s13, s45, s3
	s_add_i32 s13, s13, s12
	s_mul_i32 s12, s45, s3
	s_add_u32 s40, s12, s2
	s_addc_u32 s41, s13, s43
	v_mov_b64_e32 v[2:3], 0x6e8
	v_cmp_lt_i64_e64 s[38:39], s[40:41], v[2:3]
	v_mov_b64_e32 v[2:3], 0x6e7
	v_cmp_gt_i64_e32 vcc, s[40:41], v[2:3]
	s_cbranch_vccnz .LBB0_152
	s_ashr_i32 s12, s40, 31
	s_lshr_b32 s12, s12, 29
	s_add_i32 s12, s40, s12
	s_ashr_i32 s13, s12, 3
	s_and_b32 s12, s12, -8
	s_sub_i32 s12, s40, s12
	s_cmp_lt_i32 s12, 0
	s_movk_i32 s40, 0xde
	s_cselect_b32 s40, s40, 0xdd
	s_mul_i32 s12, s12, s40
	s_add_i32 s12, s12, s13
	s_mul_hi_i32 s13, s12, 0x4ec4ec4f
	s_lshr_b32 s40, s13, 31
	s_ashr_i32 s13, s13, 7
	s_add_i32 s13, s13, s40
	s_lshl_b32 s40, s13, 3
	s_sub_i32 s41, 34, s40
	s_min_i32 s41, s41, 8
	s_abs_i32 s66, s41
	v_cvt_f32_u32_e32 v2, s66
	s_sub_i32 s68, 0, s66
	s_mulk_i32 s13, 0x1a0
	s_sub_i32 s12, s12, s13
	v_rcp_iflag_f32_e32 v2, v2
	s_abs_i32 s13, s12
	s_xor_b32 s67, s12, s41
	s_ashr_i32 s67, s67, 31
	v_mul_f32_e32 v2, 0x4f7ffffe, v2
	v_cvt_u32_f32_e32 v2, v2
	s_nop 0
	v_readfirstlane_b32 s69, v2
	s_mul_i32 s68, s68, s69
	s_mul_hi_u32 s68, s69, s68
	s_add_i32 s69, s69, s68
	s_mul_hi_u32 s68, s13, s69
	s_mul_i32 s69, s68, s66
	s_sub_i32 s13, s13, s69
	s_add_i32 s76, s68, 1
	s_sub_i32 s69, s13, s66
	s_cmp_ge_u32 s13, s66
	s_cselect_b32 s68, s76, s68
	s_cselect_b32 s13, s69, s13
	s_add_i32 s69, s68, 1
	s_cmp_ge_u32 s13, s66
	s_cselect_b32 s13, s69, s68
	s_xor_b32 s13, s13, s67
	s_sub_i32 s82, s13, s67
	s_mul_i32 s13, s82, s41
	s_sub_i32 s12, s12, s13
	s_add_i32 s84, s40, s12

; #define PG8_SB(B) __builtin_amdgcn_rcpf(1.f + expneg(B))
; #define PG8_SB(B) __builtin_amdgcn_rcpf(1.f + expneg(B))
; #define PG8_STAGE(bufoff, gbase, voff) do { _Pragma("unroll") for (int _i = 0; _i < 2; ++_i) \
;         __builtin_amdgcn_global_load_lds((const unsigned*)((const char*)(gbase) + (size_t)_i * qstep + (voff)[0]), (PG8_LAS unsigned*)(lds + (bufoff) + ldsw + _i * 8192), 16, 0, 0); } while (0)
; #define PG8_LDA(dst, b, h) do { _Pragma("unroll") for (int m = 0; m < 4; ++m) _Pragma("unroll") for (int k = 0; k < 2; ++k) dst[m][k] = *(const PG8_LAS bf16x8*)(lds + PG8_SA(b, h) + aoff + m * 2048 + k * 1024); } while (0)
; #define PG8_LDB(dst, b, h) do { _Pragma("unroll") for (int n = 0; n < 2; ++n) _Pragma("unroll") for (int k = 0; k < 2; ++k) dst[n][k] = *(const PG8_LAS bf16x8*)(lds + PG8_SB(b, h) + boff + n * 2048 + k * 1024); } while (0)
; #define PG8_WAIT_V89() do { if constexpr (SLIVER) PG8_WAIT_V(9); else PG8_WAIT_V(8); } while (0)
; #define PG8_WAIT_L(n) asm volatile("s_waitcnt lgkmcnt(" #n ")" ::: "memory")
; template <class Epi, class Sched, bool ALIGN_EPI = false, bool SP2 = false, bool SLIVER = false>
; __device__ __forceinline__ void gemm_phase(PG8_LAS unsigned char* lds, const Gemm g, const Sched& S, const Epi& E) {
;     ...
;         for (int t = 0; t < nt; t += 2) {
;             const bool last = (t == nt - 2);
;             const char* a1 = cA + (size_t)(t + 1) * kstep;
;             const char* a2 = last ? nA : cA + (size_t)(t + 2) * kstep; const char* b2 = last ? nB : cB + (size_t)(t + 2) * kstep;
;             const char* a3 = a2 + kstep; const char* b3 = b2 + kstep;
;             const char* s1 = cS + (size_t)(t + 1) * kstep; const char* s2 = last ? nS : cS + (size_t)(t + 2) * kstep;
;             if (last && has_next) S.a_ready(nxt);
;             if constexpr (SP2) {
;             PG8_LDB(B0, 0, 0); PG8_LDB(B1, 0, 1); PG8_SCHED; PG8_LDA(At, 0, 0); PG8_STAGE(PG8_SA(1, 1), a1 + hstep, voffA); PG8_STAGE_S(1, s1);
;             PG8_WAIT_V89(); PG8_WAIT_L(0); PG8_BAR; PG8_MMA(0, 0, At, B0); PG8_MMA(0, 1, At, B1); PG8_BAR; PG8_SCHED;
;             PG8_LDA(At, 0, 1); PG8_LDS_S(0); PG8_STAGE(PG8_SB(0, 0), b2, voffB); PG8_STAGE(PG8_SB(0, 1), b2 + hstep, voffB); PG8_STAGE(PG8_SA(0, 0), a2, voffA);
;             PG8_WAIT_V89(); PG8_WAIT_L(0); PG8_BAR; PG8_MMA(1, 0, At, B0); PG8_MMA(1, 1, At, B1); PG8_MMA_S(); PG8_BAR; PG8_SCHED;
.LBB0_153:
	s_add_u32 s62, s40, 0xfff80080
	s_addc_u32 s63, s41, -1
	s_add_i32 s77, 0, 0x10000
	s_cmp_eq_u32 s76, 28
	s_cselect_b32 s63, s12, s63
	s_cselect_b32 s62, s13, s62
	v_add_u32_e32 v144, s77, v145
	s_cselect_b32 s79, s66, s69
	s_cselect_b32 s78, s67, s68
	s_add_i32 s80, 0, 0x14000
	ds_read_b128 v[136:139], v144
	ds_read_b128 v[140:143], v144 offset:1024
	ds_read_b128 v[150:153], v144 offset:2048
	ds_read_b128 v[154:157], v144 offset:3072
	v_add_u32_e32 v144, s80, v145
	ds_read_b128 v[158:161], v144
	ds_read_b128 v[162:165], v144 offset:1024
	ds_read_b128 v[166:169], v144 offset:2048
	ds_read_b128 v[170:173], v144 offset:3072
	v_lshl_add_u64 v[146:147], s[40:41], 0, v[134:135]
	s_add_i32 m0, s91, 0xc000
	ds_read_b128 v[174:177], v149
	ds_read_b128 v[180:183], v149 offset:1024
	ds_read_b128 v[184:187], v149 offset:2048
	ds_read_b128 v[188:191], v149 offset:3072
	ds_read_b128 v[192:195], v149 offset:4096
	ds_read_b128 v[196:199], v149 offset:5120
	ds_read_b128 v[200:203], v149 offset:6144
	ds_read_b128 v[210:213], v149 offset:7168
	global_load_lds_dwordx4 v[146:147], off
	v_lshl_add_u64 v[146:147], v[146:147], 0, s[20:21]
	s_add_i32 m0, s91, 0xe000
	s_nop 0
	global_load_lds_dwordx4 v[146:147], off
	s_cmp_eq_u32 s76, s101
	s_cbranch_scc1 .Lgin_skipw0
	s_waitcnt vmcnt(8)
.Lgin_skipw0:
	s_waitcnt lgkmcnt(0)
	s_barrier
	s_setprio 1
	s_waitcnt lgkmcnt(0)
	v_mfma_f32_16x16x32_bf16 v[126:129], v[136:139], v[174:177], v[126:129]
	v_mfma_f32_16x16x32_bf16 v[122:125], v[150:153], v[174:177], v[122:125]
	v_mfma_f32_16x16x32_bf16 v[114:117], v[136:139], v[184:187], v[114:117]
	v_mfma_f32_16x16x32_bf16 v[106:109], v[150:153], v[184:187], v[106:109]
	v_mfma_f32_16x16x32_bf16 v[98:101], v[136:139], v[192:195], v[98:101]
	v_mfma_f32_16x16x32_bf16 v[90:93], v[150:153], v[192:195], v[90:93]
	v_mfma_f32_16x16x32_bf16 v[82:85], v[136:139], v[200:203], v[82:85]
	v_mfma_f32_16x16x32_bf16 v[74:77], v[150:153], v[200:203], v[74:77]
	v_mfma_f32_16x16x32_bf16 v[126:129], v[140:143], v[180:183], v[126:129]
	v_mfma_f32_16x16x32_bf16 v[122:125], v[154:157], v[180:183], v[122:125]
	v_mfma_f32_16x16x32_bf16 v[114:117], v[140:143], v[188:191], v[114:117]
	v_mfma_f32_16x16x32_bf16 v[106:109], v[154:157], v[188:191], v[106:109]
	v_mfma_f32_16x16x32_bf16 v[98:101], v[140:143], v[196:199], v[98:101]
	v_mfma_f32_16x16x32_bf16 v[90:93], v[154:157], v[196:199], v[90:93]
	v_mfma_f32_16x16x32_bf16 v[82:85], v[140:143], v[210:213], v[82:85]
	v_mfma_f32_16x16x32_bf16 v[74:77], v[154:157], v[210:213], v[74:77]
	s_setprio 0
	s_setprio 1
	v_mfma_f32_16x16x32_bf16 v[118:121], v[158:161], v[174:177], v[118:121]
	v_mfma_f32_16x16x32_bf16 v[110:113], v[166:169], v[174:177], v[110:113]
	v_mfma_f32_16x16x32_bf16 v[102:105], v[158:161], v[184:187], v[102:105]
	v_mfma_f32_16x16x32_bf16 v[94:97], v[166:169], v[184:187], v[94:97]
	v_mfma_f32_16x16x32_bf16 v[86:89], v[158:161], v[192:195], v[86:89]
	v_mfma_f32_16x16x32_bf16 v[78:81], v[166:169], v[192:195], v[78:81]
	v_mfma_f32_16x16x32_bf16 v[70:73], v[158:161], v[200:203], v[70:73]
	v_mfma_f32_16x16x32_bf16 v[66:69], v[166:169], v[200:203], v[66:69]
	v_mfma_f32_16x16x32_bf16 v[118:121], v[162:165], v[180:183], v[118:121]
	v_mfma_f32_16x16x32_bf16 v[110:113], v[170:173], v[180:183], v[110:113]
	v_mfma_f32_16x16x32_bf16 v[102:105], v[162:165], v[188:191], v[102:105]
	v_mfma_f32_16x16x32_bf16 v[94:97], v[170:173], v[188:191], v[94:97]
	v_mfma_f32_16x16x32_bf16 v[86:89], v[162:165], v[196:199], v[86:89]
	v_mfma_f32_16x16x32_bf16 v[78:81], v[170:173], v[196:199], v[78:81]
	v_mfma_f32_16x16x32_bf16 v[70:73], v[162:165], v[210:213], v[70:73]
	v_mfma_f32_16x16x32_bf16 v[66:69], v[170:173], v[210:213], v[66:69]
	s_setprio 0
	s_barrier
	s_add_i32 s77, s77, s53
	v_lshl_add_u64 v[146:147], s[78:79], 0, v[132:133]
	s_mov_b32 m0, s77
	ds_read_b128 v[174:177], v149 offset:16384
	ds_read_b128 v[180:183], v149 offset:17408
	ds_read_b128 v[184:187], v149 offset:18432
	ds_read_b128 v[188:191], v149 offset:19456
	ds_read_b128 v[192:195], v149 offset:20480
	ds_read_b128 v[196:199], v149 offset:21504
	ds_read_b128 v[200:203], v149 offset:22528
	ds_read_b128 v[210:213], v149 offset:23552
	global_load_lds_dwordx4 v[146:147], off
	v_lshl_add_u64 v[214:215], v[146:147], 0, s[20:21]
	s_add_i32 m0, s77, 0x2000
	s_add_i32 s77, s80, s53
	global_load_lds_dwordx4 v[214:215], off
	v_lshl_add_u64 v[214:215], v[146:147], 0, s[22:23]
	s_mov_b32 m0, s77
	s_nop 0
	global_load_lds_dwordx4 v[214:215], off
	v_lshl_add_u64 v[214:215], v[146:147], 0, s[24:25]
	s_add_i32 m0, s77, 0x2000
	s_nop 0
	global_load_lds_dwordx4 v[214:215], off
	v_lshl_add_u64 v[214:215], s[62:63], 0, v[130:131]
	s_mov_b32 m0, s91
	v_lshl_add_u64 v[216:217], v[214:215], 0, s[20:21]
	global_load_lds_dwordx4 v[214:215], off
	s_mov_b32 m0, s50
	s_nop 0
	global_load_lds_dwordx4 v[216:217], off
	s_cmp_eq_u32 s76, s101
	s_cbranch_scc1 .Lgin_skipw1
	s_waitcnt vmcnt(8)
; #define PG8_STAGE(bufoff, gbase, voff) do { _Pragma("unroll") for (int _i = 0; _i < 2; ++_i) \
;         __builtin_amdgcn_global_load_lds((const unsigned*)((const char*)(gbase) + (size_t)_i * qstep + (voff)[0]), (PG8_LAS unsigned*)(lds + (bufoff) + ldsw + _i * 8192), 16, 0, 0); } while (0)
; #define PG8_LDA(dst, b, h) do { _Pragma("unroll") for (int m = 0; m < 4; ++m) _Pragma("unroll") for (int k = 0; k < 2; ++k) dst[m][k] = *(const PG8_LAS bf16x8*)(lds + PG8_SA(b, h) + aoff + m * 2048 + k * 1024); } while (0)
; #define PG8_LDB(dst, b, h) do { _Pragma("unroll") for (int n = 0; n < 2; ++n) _Pragma("unroll") for (int k = 0; k < 2; ++k) dst[n][k] = *(const PG8_LAS bf16x8*)(lds + PG8_SB(b, h) + boff + n * 2048 + k * 1024); } while (0)
; #define PG8_MMA(ai, bj, At, Bt) do { __builtin_amdgcn_s_setprio(1); _Pragma("unroll") for (int m = 0; m < 4; ++m) _Pragma("unroll") for (int n = 0; n < 2; ++n) _Pragma("unroll") for (int k = 0; k < 2; ++k) \
;         acc[ai][bj][m][n] = __builtin_amdgcn_mfma_f32_16x16x32_bf16(Bt[n][k], At[m][k], acc[ai][bj][m][n], 0, 0, 0); __builtin_amdgcn_s_setprio(0); } while (0)
; #define PG8_WAIT_V89() do { if constexpr (SLIVER) PG8_WAIT_V(9); else PG8_WAIT_V(8); } while (0)
; #define PG8_STAGE_S(b, gbase) do { if constexpr (SLIVER) __builtin_amdgcn_global_load_lds((const unsigned*)((const char*)(gbase) + voffS), (PG8_LAS unsigned*)(lds + STAGE_BYTES + (b) * 2048 + wid * 256), 4, 0, 0); } while (0)
; #define PG8_WAIT_L(n) asm volatile("s_waitcnt lgkmcnt(" #n ")" ::: "memory")
; #define PG8_BAR __builtin_amdgcn_s_barrier()
; #define PG8_SCHED __builtin_amdgcn_sched_barrier(0)
; template <class Epi, class Sched, bool ALIGN_EPI = false, bool SP2 = false, bool SLIVER = false>
; __device__ __forceinline__ void gemm_phase(PG8_LAS unsigned char* lds, const Gemm g, const Sched& S, const Epi& E) {
;     ...
;             PG8_WAIT_V89(); PG8_WAIT_L(0); PG8_BAR; PG8_MMA(1, 0, At, B0); PG8_MMA(1, 1, At, B1); PG8_MMA_S(); PG8_BAR; PG8_SCHED;
;             PG8_LDB(B0, 1, 0); PG8_LDB(B1, 1, 1); PG8_SCHED; PG8_LDA(At, 1, 0); PG8_STAGE(PG8_SA(0, 1), a2 + hstep, voffA); PG8_STAGE_S(0, s2);
;             PG8_WAIT_V89(); PG8_WAIT_L(0); PG8_BAR; PG8_MMA(0, 0, At, B0); PG8_MMA(0, 1, At, B1); PG8_BAR; PG8_SCHED;
.Lgin_skipw1:
	s_waitcnt lgkmcnt(0)
	s_barrier
	s_setprio 1
	s_waitcnt lgkmcnt(0)
	v_mfma_f32_16x16x32_bf16 v[62:65], v[136:139], v[174:177], v[62:65]
	v_mfma_f32_16x16x32_bf16 v[58:61], v[150:153], v[174:177], v[58:61]
	v_mfma_f32_16x16x32_bf16 v[50:53], v[136:139], v[184:187], v[50:53]
	v_mfma_f32_16x16x32_bf16 v[42:45], v[150:153], v[184:187], v[42:45]
	v_mfma_f32_16x16x32_bf16 v[34:37], v[136:139], v[192:195], v[34:37]
	v_mfma_f32_16x16x32_bf16 v[26:29], v[150:153], v[192:195], v[26:29]
	v_mfma_f32_16x16x32_bf16 v[18:21], v[136:139], v[200:203], v[18:21]
	v_mfma_f32_16x16x32_bf16 v[10:13], v[150:153], v[200:203], v[10:13]
	v_mfma_f32_16x16x32_bf16 v[62:65], v[140:143], v[180:183], v[62:65]
	v_mfma_f32_16x16x32_bf16 v[58:61], v[154:157], v[180:183], v[58:61]
	v_mfma_f32_16x16x32_bf16 v[50:53], v[140:143], v[188:191], v[50:53]
	v_mfma_f32_16x16x32_bf16 v[42:45], v[154:157], v[188:191], v[42:45]
	v_mfma_f32_16x16x32_bf16 v[34:37], v[140:143], v[196:199], v[34:37]
	v_mfma_f32_16x16x32_bf16 v[26:29], v[154:157], v[196:199], v[26:29]
	v_mfma_f32_16x16x32_bf16 v[18:21], v[140:143], v[210:213], v[18:21]
	v_mfma_f32_16x16x32_bf16 v[10:13], v[154:157], v[210:213], v[10:13]
	s_setprio 0
	s_setprio 1
	v_mfma_f32_16x16x32_bf16 v[54:57], v[158:161], v[174:177], v[54:57]
	v_mfma_f32_16x16x32_bf16 v[46:49], v[166:169], v[174:177], v[46:49]
	v_mfma_f32_16x16x32_bf16 v[38:41], v[158:161], v[184:187], v[38:41]
	v_mfma_f32_16x16x32_bf16 v[30:33], v[166:169], v[184:187], v[30:33]
	v_mfma_f32_16x16x32_bf16 v[22:25], v[158:161], v[192:195], v[22:25]
	v_mfma_f32_16x16x32_bf16 v[14:17], v[166:169], v[192:195], v[14:17]
	v_mfma_f32_16x16x32_bf16 v[6:9], v[158:161], v[200:203], v[6:9]
	v_mfma_f32_16x16x32_bf16 v[2:5], v[166:169], v[200:203], v[2:5]
	v_mfma_f32_16x16x32_bf16 v[54:57], v[162:165], v[180:183], v[54:57]
	v_mfma_f32_16x16x32_bf16 v[46:49], v[170:173], v[180:183], v[46:49]
	v_mfma_f32_16x16x32_bf16 v[38:41], v[162:165], v[188:191], v[38:41]
	v_mfma_f32_16x16x32_bf16 v[30:33], v[170:173], v[188:191], v[30:33]
	v_mfma_f32_16x16x32_bf16 v[22:25], v[162:165], v[196:199], v[22:25]
	v_mfma_f32_16x16x32_bf16 v[14:17], v[170:173], v[196:199], v[14:17]
	v_mfma_f32_16x16x32_bf16 v[6:9], v[162:165], v[210:213], v[6:9]
	v_mfma_f32_16x16x32_bf16 v[2:5], v[170:173], v[210:213], v[2:5]
	s_setprio 0
	s_barrier
	s_add_i32 s62, 0, 0x18000
	v_add_u32_e32 v144, s62, v145
	s_add_i32 s63, 0, 0x1c000
	ds_read_b128 v[136:139], v144
	ds_read_b128 v[140:143], v144 offset:1024
	ds_read_b128 v[150:153], v144 offset:2048
	ds_read_b128 v[154:157], v144 offset:3072
	v_add_u32_e32 v144, s63, v145
	ds_read_b128 v[158:161], v144
	ds_read_b128 v[162:165], v144 offset:1024
	ds_read_b128 v[166:169], v144 offset:2048
	ds_read_b128 v[170:173], v144 offset:3072
	s_mov_b32 m0, s51
	v_lshl_add_u64 v[216:217], v[214:215], 0, s[22:23]
	ds_read_b128 v[174:177], v149 offset:32768
	ds_read_b128 v[180:183], v149 offset:33792
	ds_read_b128 v[184:187], v149 offset:34816
	ds_read_b128 v[188:191], v149 offset:35840
	ds_read_b128 v[192:195], v149 offset:36864
	ds_read_b128 v[196:199], v149 offset:37888
	ds_read_b128 v[200:203], v149 offset:38912
	ds_read_b128 v[210:213], v149 offset:39936
	global_load_lds_dwordx4 v[216:217], off
	v_lshl_add_u64 v[216:217], v[214:215], 0, s[24:25]
	s_mov_b32 m0, s54
	s_nop 0
	global_load_lds_dwordx4 v[216:217], off
	s_waitcnt vmcnt(8)
	s_waitcnt lgkmcnt(0)
	s_barrier
	s_setprio 1
	s_waitcnt lgkmcnt(0)
	v_mfma_f32_16x16x32_bf16 v[126:129], v[136:139], v[174:177], v[126:129]
	v_mfma_f32_16x16x32_bf16 v[122:125], v[150:153], v[174:177], v[122:125]
	v_mfma_f32_16x16x32_bf16 v[114:117], v[136:139], v[184:187], v[114:117]
	v_mfma_f32_16x16x32_bf16 v[106:109], v[150:153], v[184:187], v[106:109]
	v_mfma_f32_16x16x32_bf16 v[98:101], v[136:139], v[192:195], v[98:101]
	v_mfma_f32_16x16x32_bf16 v[90:93], v[150:153], v[192:195], v[90:93]
	v_mfma_f32_16x16x32_bf16 v[82:85], v[136:139], v[200:203], v[82:85]
	v_mfma_f32_16x16x32_bf16 v[74:77], v[150:153], v[200:203], v[74:77]
	v_mfma_f32_16x16x32_bf16 v[126:129], v[140:143], v[180:183], v[126:129]
	v_mfma_f32_16x16x32_bf16 v[122:125], v[154:157], v[180:183], v[122:125]
	v_mfma_f32_16x16x32_bf16 v[114:117], v[140:143], v[188:191], v[114:117]
	v_mfma_f32_16x16x32_bf16 v[106:109], v[154:157], v[188:191], v[106:109]
	v_mfma_f32_16x16x32_bf16 v[98:101], v[140:143], v[196:199], v[98:101]
	v_mfma_f32_16x16x32_bf16 v[90:93], v[154:157], v[196:199], v[90:93]
	v_mfma_f32_16x16x32_bf16 v[82:85], v[140:143], v[210:213], v[82:85]
	v_mfma_f32_16x16x32_bf16 v[74:77], v[154:157], v[210:213], v[74:77]
	s_setprio 0
	s_setprio 1
	v_mfma_f32_16x16x32_bf16 v[118:121], v[158:161], v[174:177], v[118:121]
	v_mfma_f32_16x16x32_bf16 v[110:113], v[166:169], v[174:177], v[110:113]
	v_mfma_f32_16x16x32_bf16 v[102:105], v[158:161], v[184:187], v[102:105]
	v_mfma_f32_16x16x32_bf16 v[94:97], v[166:169], v[184:187], v[94:97]
	v_mfma_f32_16x16x32_bf16 v[86:89], v[158:161], v[192:195], v[86:89]
	v_mfma_f32_16x16x32_bf16 v[78:81], v[166:169], v[192:195], v[78:81]
	v_mfma_f32_16x16x32_bf16 v[70:73], v[158:161], v[200:203], v[70:73]
	v_mfma_f32_16x16x32_bf16 v[66:69], v[166:169], v[200:203], v[66:69]
	v_mfma_f32_16x16x32_bf16 v[118:121], v[162:165], v[180:183], v[118:121]
	v_mfma_f32_16x16x32_bf16 v[110:113], v[170:173], v[180:183], v[110:113]
	v_mfma_f32_16x16x32_bf16 v[102:105], v[162:165], v[188:191], v[102:105]
	v_mfma_f32_16x16x32_bf16 v[94:97], v[170:173], v[188:191], v[94:97]
	v_mfma_f32_16x16x32_bf16 v[86:89], v[162:165], v[196:199], v[86:89]
	v_mfma_f32_16x16x32_bf16 v[78:81], v[170:173], v[196:199], v[78:81]
	v_mfma_f32_16x16x32_bf16 v[70:73], v[162:165], v[210:213], v[70:73]
	v_mfma_f32_16x16x32_bf16 v[66:69], v[170:173], v[210:213], v[66:69]
	s_setprio 0
	s_barrier
; #define PG8_SB(B) __builtin_amdgcn_rcpf(1.f + expneg(B))
; #define PG8_SB(B) __builtin_amdgcn_rcpf(1.f + expneg(B))
; #define PG8_STAGE(bufoff, gbase, voff) do { _Pragma("unroll") for (int _i = 0; _i < 2; ++_i) \
;         __builtin_amdgcn_global_load_lds((const unsigned*)((const char*)(gbase) + (size_t)_i * qstep + (voff)[0]), (PG8_LAS unsigned*)(lds + (bufoff) + ldsw + _i * 8192), 16, 0, 0); } while (0)
; #define PG8_LDA(dst, b, h) do { _Pragma("unroll") for (int m = 0; m < 4; ++m) _Pragma("unroll") for (int k = 0; k < 2; ++k) dst[m][k] = *(const PG8_LAS bf16x8*)(lds + PG8_SA(b, h) + aoff + m * 2048 + k * 1024); } while (0)
; #define PG8_MMA(ai, bj, At, Bt) do { __builtin_amdgcn_s_setprio(1); _Pragma("unroll") for (int m = 0; m < 4; ++m) _Pragma("unroll") for (int n = 0; n < 2; ++n) _Pragma("unroll") for (int k = 0; k < 2; ++k) \
;         acc[ai][bj][m][n] = __builtin_amdgcn_mfma_f32_16x16x32_bf16(Bt[n][k], At[m][k], acc[ai][bj][m][n], 0, 0, 0); __builtin_amdgcn_s_setprio(0); } while (0)
; #define PG8_WAIT_V89() do { if constexpr (SLIVER) PG8_WAIT_V(9); else PG8_WAIT_V(8); } while (0)
; #define PG8_LDS_S(b) do { if constexpr (SLIVER) { Sf[0] = *(const PG8_LAS bf16x8*)(lds + STAGE_BYTES + (b) * 2048 + soff0); Sf[1] = *(const PG8_LAS bf16x8*)(lds + STAGE_BYTES + (b) * 2048 + (soff0 ^ 64)); } } while (0)
; #define PG8_WAIT_L(n) asm volatile("s_waitcnt lgkmcnt(" #n ")" ::: "memory")
; #define PG8_BAR __builtin_amdgcn_s_barrier()
; #define PG8_SCHED __builtin_amdgcn_sched_barrier(0)
; template <class Epi, class Sched, bool ALIGN_EPI = false, bool SP2 = false, bool SLIVER = false>
; __device__ __forceinline__ void gemm_phase(PG8_LAS unsigned char* lds, const Gemm g, const Sched& S, const Epi& E) {
;     ...
;             PG8_LDA(At, 1, 1); PG8_LDS_S(1); PG8_STAGE(PG8_SB(1, 0), b3, voffB); PG8_STAGE(PG8_SB(1, 1), b3 + hstep, voffB); PG8_STAGE(PG8_SA(1, 0), a3, voffA);
;             PG8_WAIT_V89(); PG8_WAIT_L(0); PG8_BAR; PG8_MMA(1, 0, At, B0); PG8_MMA(1, 1, At, B1); PG8_MMA_S(); PG8_BAR; PG8_SCHED;
;     ...
;         if constexpr (ALIGN_EPI) { if (wr == 0) PG8_BAR; }
	s_add_i32 s62, s62, s53
	v_lshl_add_u64 v[216:217], v[146:147], 0, s[26:27]
	s_mov_b32 m0, s62
	ds_read_b128 v[174:177], v149 offset:49152
	ds_read_b128 v[180:183], v149 offset:50176
	ds_read_b128 v[184:187], v149 offset:51200
	ds_read_b128 v[188:191], v149 offset:52224
	ds_read_b128 v[192:195], v149 offset:53248
	ds_read_b128 v[196:199], v149 offset:54272
	ds_read_b128 v[200:203], v149 offset:55296
	ds_read_b128 v[210:213], v149 offset:56320
	global_load_lds_dwordx4 v[216:217], off
	v_lshl_add_u64 v[216:217], v[146:147], 0, s[28:29]
	s_add_i32 m0, s62, 0x2000
	s_add_i32 s62, s63, s53
	global_load_lds_dwordx4 v[216:217], off
	v_lshl_add_u64 v[216:217], v[146:147], 0, s[30:31]
	s_mov_b32 m0, s62
	v_lshl_add_u64 v[146:147], v[146:147], 0, s[34:35]
	global_load_lds_dwordx4 v[216:217], off
	s_add_i32 m0, s62, 0x2000
	s_nop 0
	global_load_lds_dwordx4 v[146:147], off
	v_lshl_add_u64 v[146:147], v[214:215], 0, s[26:27]
	s_mov_b32 m0, s10
	s_nop 0
	global_load_lds_dwordx4 v[146:147], off
	v_lshl_add_u64 v[146:147], v[214:215], 0, s[28:29]
	s_mov_b32 m0, s55
	s_nop 0
	global_load_lds_dwordx4 v[146:147], off
	s_waitcnt vmcnt(8)
	s_waitcnt lgkmcnt(0)
	s_barrier
	s_setprio 1
	s_waitcnt lgkmcnt(0)
	v_mfma_f32_16x16x32_bf16 v[62:65], v[136:139], v[174:177], v[62:65]
	v_mfma_f32_16x16x32_bf16 v[58:61], v[150:153], v[174:177], v[58:61]
	v_mfma_f32_16x16x32_bf16 v[50:53], v[136:139], v[184:187], v[50:53]
	v_mfma_f32_16x16x32_bf16 v[42:45], v[150:153], v[184:187], v[42:45]
	v_mfma_f32_16x16x32_bf16 v[34:37], v[136:139], v[192:195], v[34:37]
	v_mfma_f32_16x16x32_bf16 v[26:29], v[150:153], v[192:195], v[26:29]
	v_mfma_f32_16x16x32_bf16 v[18:21], v[136:139], v[200:203], v[18:21]
	v_mfma_f32_16x16x32_bf16 v[10:13], v[150:153], v[200:203], v[10:13]
	v_mfma_f32_16x16x32_bf16 v[62:65], v[140:143], v[180:183], v[62:65]
	v_mfma_f32_16x16x32_bf16 v[58:61], v[154:157], v[180:183], v[58:61]
	v_mfma_f32_16x16x32_bf16 v[50:53], v[140:143], v[188:191], v[50:53]
	v_mfma_f32_16x16x32_bf16 v[42:45], v[154:157], v[188:191], v[42:45]
	v_mfma_f32_16x16x32_bf16 v[34:37], v[140:143], v[196:199], v[34:37]
	v_mfma_f32_16x16x32_bf16 v[26:29], v[154:157], v[196:199], v[26:29]
	v_mfma_f32_16x16x32_bf16 v[18:21], v[140:143], v[210:213], v[18:21]
	v_mfma_f32_16x16x32_bf16 v[10:13], v[154:157], v[210:213], v[10:13]
	s_setprio 0
	s_setprio 1
	v_mfma_f32_16x16x32_bf16 v[54:57], v[158:161], v[174:177], v[54:57]
	v_mfma_f32_16x16x32_bf16 v[46:49], v[166:169], v[174:177], v[46:49]
	v_mfma_f32_16x16x32_bf16 v[38:41], v[158:161], v[184:187], v[38:41]
	v_mfma_f32_16x16x32_bf16 v[30:33], v[166:169], v[184:187], v[30:33]
	v_mfma_f32_16x16x32_bf16 v[22:25], v[158:161], v[192:195], v[22:25]
	v_mfma_f32_16x16x32_bf16 v[14:17], v[166:169], v[192:195], v[14:17]
	v_mfma_f32_16x16x32_bf16 v[6:9], v[158:161], v[200:203], v[6:9]
	v_mfma_f32_16x16x32_bf16 v[2:5], v[166:169], v[200:203], v[2:5]
	v_mfma_f32_16x16x32_bf16 v[54:57], v[162:165], v[180:183], v[54:57]
	v_mfma_f32_16x16x32_bf16 v[46:49], v[170:173], v[180:183], v[46:49]
	v_mfma_f32_16x16x32_bf16 v[38:41], v[162:165], v[188:191], v[38:41]
	v_mfma_f32_16x16x32_bf16 v[30:33], v[170:173], v[188:191], v[30:33]
	v_mfma_f32_16x16x32_bf16 v[22:25], v[162:165], v[196:199], v[22:25]
	v_mfma_f32_16x16x32_bf16 v[14:17], v[170:173], v[196:199], v[14:17]
	v_mfma_f32_16x16x32_bf16 v[6:9], v[162:165], v[210:213], v[6:9]
	v_mfma_f32_16x16x32_bf16 v[2:5], v[170:173], v[210:213], v[2:5]
	s_setprio 0
	s_barrier
	s_add_i32 s76, s76, 2
	s_add_u32 s40, s40, 0x100
	s_addc_u32 s41, s41, 0
	s_add_u32 s68, s68, 0x100
	s_addc_u32 s69, s69, 0
	s_cmp_gt_u32 s76, 29
	s_cbranch_scc0 .LBB0_153
	s_and_b64 vcc, exec, s[48:49]
	s_cbranch_vccz .LBB0_156
	s_barrier

;     __host__ __device__ bool next(int i, Unit& u) const {
;         const int rnd = nseg == 1 ? i : (i >> 1); u.seg = nseg == 1 ? 0 : (i & 1);
;         const long L = (long)rnd * G + c; if (L >= nwg) return false;
;         int wgid = (int)L; { const int q = nwg / NXCD, r = nwg % NXCD, xcd = wgid % NXCD, off = wgid / NXCD; wgid = (xcd < r ? xcd * (q + 1) : r * (q + 1) + (xcd - r) * q) + off; }
;         const int nig = WGM * nN, gid = wgid / nig, fm = gid * WGM, gsz = (nM - fm) < WGM ? (nM - fm) : WGM;
;         u.pm = fm + ((wgid % nig) % gsz); u.pn = (wgid % nig) / gsz; return true;
; template <class Epi, class Sched, bool ALIGN_EPI = false, bool SP2 = false, bool SLIVER = false>
; __device__ __forceinline__ void gemm_phase(PG8_LAS unsigned char* lds, const Gemm g, const Sched& S, const Epi& E) {
;     ...
;         const bool has_next = S.next(ui + 1, nxt);
.LBB0_702:
	s_add_i32 s96, s96, 1
	s_cmp_gt_u32 s96, 1
	s_cselect_b32 s101, -2, 0x7ffffff0
	s_mul_i32 s3, s96, s95
	s_mul_hi_u32 s38, s96, s13
	s_add_i32 s38, s38, s3
	s_mul_i32 s3, s96, s13
	s_add_u32 s52, s3, s12
	s_addc_u32 s53, s38, s89
	v_mov_b64_e32 v[2:3], 0x5d8
	v_cmp_lt_i64_e64 s[38:39], s[52:53], v[2:3]
	v_mov_b64_e32 v[2:3], 0x5d7
	v_cmp_gt_i64_e32 vcc, s[52:53], v[2:3]
	s_cbranch_vccnz .LBB0_704
	s_ashr_i32 s3, s52, 31
	s_lshr_b32 s3, s3, 29
	s_add_i32 s3, s52, s3
	s_ashr_i32 s48, s3, 3
	s_and_b32 s3, s3, -8
	s_sub_i32 s3, s52, s3
	s_cmp_lt_i32 s3, 0
	s_movk_i32 s49, 0xbc
	s_cselect_b32 s49, s49, 0xbb
	s_mul_i32 s3, s3, s49
	s_add_i32 s3, s3, s48
	s_mul_hi_i32 s48, s3, 0x2e8ba2e9
	s_lshr_b32 s49, s48, 31
	s_ashr_i32 s48, s48, 6
	s_add_i32 s48, s48, s49
	s_lshl_b32 s49, s48, 3
	s_sub_i32 s50, 34, s49
	s_min_i32 s50, s50, 8
	s_abs_i32 s51, s50
	v_cvt_f32_u32_e32 v2, s51
	s_sub_i32 s53, 0, s51
	s_mulk_i32 s48, 0x160
	s_sub_i32 s3, s3, s48
	v_rcp_iflag_f32_e32 v2, v2
	s_abs_i32 s48, s3
	s_xor_b32 s52, s3, s50
	s_ashr_i32 s52, s52, 31
	v_mul_f32_e32 v2, 0x4f7ffffe, v2
	v_cvt_u32_f32_e32 v2, v2
	s_nop 0
	v_readfirstlane_b32 s54, v2
	s_mul_i32 s53, s53, s54
	s_mul_hi_u32 s53, s54, s53
	s_add_i32 s54, s54, s53
	s_mul_hi_u32 s53, s48, s54
	s_mul_i32 s54, s53, s51
	s_sub_i32 s48, s48, s54
	s_add_i32 s55, s53, 1
	s_sub_i32 s54, s48, s51
	s_cmp_ge_u32 s48, s51
	s_cselect_b32 s53, s55, s53
	s_cselect_b32 s48, s54, s48
	s_add_i32 s54, s53, 1
	s_cmp_ge_u32 s48, s51
	s_cselect_b32 s48, s54, s53
	s_xor_b32 s48, s48, s52
	s_sub_i32 s48, s48, s52
	s_mul_i32 s50, s48, s50
	s_sub_i32 s3, s3, s50
	s_add_i32 s50, s49, s3

; #define PG8_SB(B) __builtin_amdgcn_rcpf(1.f + expneg(B))
; #define PG8_SB(B) __builtin_amdgcn_rcpf(1.f + expneg(B))
; #define PG8_STAGE(bufoff, gbase, voff) do { _Pragma("unroll") for (int _i = 0; _i < 2; ++_i) \
;         __builtin_amdgcn_global_load_lds((const unsigned*)((const char*)(gbase) + (size_t)_i * qstep + (voff)[0]), (PG8_LAS unsigned*)(lds + (bufoff) + ldsw + _i * 8192), 16, 0, 0); } while (0)
; #define PG8_LDA(dst, b, h) do { _Pragma("unroll") for (int m = 0; m < 4; ++m) _Pragma("unroll") for (int k = 0; k < 2; ++k) dst[m][k] = *(const PG8_LAS bf16x8*)(lds + PG8_SA(b, h) + aoff + m * 2048 + k * 1024); } while (0)
; #define PG8_LDB(dst, b, h) do { _Pragma("unroll") for (int n = 0; n < 2; ++n) _Pragma("unroll") for (int k = 0; k < 2; ++k) dst[n][k] = *(const PG8_LAS bf16x8*)(lds + PG8_SB(b, h) + boff + n * 2048 + k * 1024); } while (0)
; #define PG8_WAIT_V89() do { if constexpr (SLIVER) PG8_WAIT_V(9); else PG8_WAIT_V(8); } while (0)
; #define PG8_WAIT_L(n) asm volatile("s_waitcnt lgkmcnt(" #n ")" ::: "memory")
; template <class Epi, class Sched, bool ALIGN_EPI = false, bool SP2 = false, bool SLIVER = false>
; __device__ __forceinline__ void gemm_phase(PG8_LAS unsigned char* lds, const Gemm g, const Sched& S, const Epi& E) {
;     ...
;         for (int t = 0; t < nt; t += 2) {
;             const bool last = (t == nt - 2);
;             const char* a1 = cA + (size_t)(t + 1) * kstep;
;             const char* a2 = last ? nA : cA + (size_t)(t + 2) * kstep; const char* b2 = last ? nB : cB + (size_t)(t + 2) * kstep;
;             const char* a3 = a2 + kstep; const char* b3 = b2 + kstep;
;             const char* s1 = cS + (size_t)(t + 1) * kstep; const char* s2 = last ? nS : cS + (size_t)(t + 2) * kstep;
;             if (last && has_next) S.a_ready(nxt);
;             if constexpr (SP2) {
;             PG8_LDB(B0, 0, 0); PG8_LDB(B1, 0, 1); PG8_SCHED; PG8_LDA(At, 0, 0); PG8_STAGE(PG8_SA(1, 1), a1 + hstep, voffA); PG8_STAGE_S(1, s1);
;             PG8_WAIT_V89(); PG8_WAIT_L(0); PG8_BAR; PG8_MMA(0, 0, At, B0); PG8_MMA(0, 1, At, B1); PG8_BAR; PG8_SCHED;
;             PG8_LDA(At, 0, 1); PG8_LDS_S(0); PG8_STAGE(PG8_SB(0, 0), b2, voffB); PG8_STAGE(PG8_SB(0, 1), b2 + hstep, voffB); PG8_STAGE(PG8_SA(0, 0), a2, voffA);
;             PG8_WAIT_V89(); PG8_WAIT_L(0); PG8_BAR; PG8_MMA(1, 0, At, B0); PG8_MMA(1, 1, At, B1); PG8_MMA_S(); PG8_BAR; PG8_SCHED;
.LBB0_705:
	s_add_u32 s76, s62, 0xfff80080
	s_addc_u32 s77, s63, -1
	s_add_i32 s78, 0, 0x10000
	s_cmp_eq_u32 s69, 28
	s_cselect_b32 s81, s3, s77
	s_cselect_b32 s80, s51, s76
	v_add_u32_e32 v142, s78, v143
	s_cselect_b32 s77, s49, s68
	s_cselect_b32 s76, s66, s67
	s_add_i32 s79, 0, 0x14000
	ds_read_b128 v[130:133], v142
	ds_read_b128 v[138:141], v142 offset:1024
	ds_read_b128 v[148:151], v142 offset:2048
	ds_read_b128 v[152:155], v142 offset:3072
	v_add_u32_e32 v142, s79, v143
	ds_read_b128 v[156:159], v142
	ds_read_b128 v[160:163], v142 offset:1024
	ds_read_b128 v[164:167], v142 offset:2048
	ds_read_b128 v[168:171], v142 offset:3072
	v_lshl_add_u64 v[144:145], s[62:63], 0, v[136:137]
	s_add_i32 m0, s45, 0xc000
	ds_read_b128 v[172:175], v147
	ds_read_b128 v[180:183], v147 offset:1024
	ds_read_b128 v[184:187], v147 offset:2048
	ds_read_b128 v[188:191], v147 offset:3072
	ds_read_b128 v[192:195], v147 offset:4096
	ds_read_b128 v[196:199], v147 offset:5120
	ds_read_b128 v[200:203], v147 offset:6144
	ds_read_b128 v[210:213], v147 offset:7168
	global_load_lds_dwordx4 v[144:145], off
	v_lshl_add_u64 v[144:145], v[144:145], 0, s[20:21]
	s_add_i32 m0, s45, 0xe000
	s_nop 0
	global_load_lds_dwordx4 v[144:145], off
	s_cmp_eq_u32 s69, s101
	s_cbranch_scc1 .Lgup_skipw0
	s_waitcnt vmcnt(8)
.Lgup_skipw0:
	s_waitcnt lgkmcnt(0)
	s_barrier
	s_setprio 1
	s_waitcnt lgkmcnt(0)
	v_mfma_f32_16x16x32_bf16 v[126:129], v[130:133], v[172:175], v[126:129]
	v_mfma_f32_16x16x32_bf16 v[118:121], v[148:151], v[172:175], v[118:121]
	v_mfma_f32_16x16x32_bf16 v[110:113], v[130:133], v[184:187], v[110:113]
	v_mfma_f32_16x16x32_bf16 v[102:105], v[148:151], v[184:187], v[102:105]
	v_mfma_f32_16x16x32_bf16 v[94:97], v[130:133], v[192:195], v[94:97]
	v_mfma_f32_16x16x32_bf16 v[86:89], v[148:151], v[192:195], v[86:89]
	v_mfma_f32_16x16x32_bf16 v[78:81], v[130:133], v[200:203], v[78:81]
	v_mfma_f32_16x16x32_bf16 v[70:73], v[148:151], v[200:203], v[70:73]
	v_mfma_f32_16x16x32_bf16 v[126:129], v[138:141], v[180:183], v[126:129]
	v_mfma_f32_16x16x32_bf16 v[118:121], v[152:155], v[180:183], v[118:121]
	v_mfma_f32_16x16x32_bf16 v[110:113], v[138:141], v[188:191], v[110:113]
	v_mfma_f32_16x16x32_bf16 v[102:105], v[152:155], v[188:191], v[102:105]
	v_mfma_f32_16x16x32_bf16 v[94:97], v[138:141], v[196:199], v[94:97]
	v_mfma_f32_16x16x32_bf16 v[86:89], v[152:155], v[196:199], v[86:89]
	v_mfma_f32_16x16x32_bf16 v[78:81], v[138:141], v[210:213], v[78:81]
	v_mfma_f32_16x16x32_bf16 v[70:73], v[152:155], v[210:213], v[70:73]
	s_setprio 0
	s_setprio 1
	v_mfma_f32_16x16x32_bf16 v[122:125], v[156:159], v[172:175], v[122:125]
	v_mfma_f32_16x16x32_bf16 v[114:117], v[164:167], v[172:175], v[114:117]
	v_mfma_f32_16x16x32_bf16 v[106:109], v[156:159], v[184:187], v[106:109]
	v_mfma_f32_16x16x32_bf16 v[98:101], v[164:167], v[184:187], v[98:101]
	v_mfma_f32_16x16x32_bf16 v[90:93], v[156:159], v[192:195], v[90:93]
	v_mfma_f32_16x16x32_bf16 v[82:85], v[164:167], v[192:195], v[82:85]
	v_mfma_f32_16x16x32_bf16 v[74:77], v[156:159], v[200:203], v[74:77]
	v_mfma_f32_16x16x32_bf16 v[66:69], v[164:167], v[200:203], v[66:69]
	v_mfma_f32_16x16x32_bf16 v[122:125], v[160:163], v[180:183], v[122:125]
	v_mfma_f32_16x16x32_bf16 v[114:117], v[168:171], v[180:183], v[114:117]
	v_mfma_f32_16x16x32_bf16 v[106:109], v[160:163], v[188:191], v[106:109]
	v_mfma_f32_16x16x32_bf16 v[98:101], v[168:171], v[188:191], v[98:101]
	v_mfma_f32_16x16x32_bf16 v[90:93], v[160:163], v[196:199], v[90:93]
	v_mfma_f32_16x16x32_bf16 v[82:85], v[168:171], v[196:199], v[82:85]
	v_mfma_f32_16x16x32_bf16 v[74:77], v[160:163], v[210:213], v[74:77]
	v_mfma_f32_16x16x32_bf16 v[66:69], v[168:171], v[210:213], v[66:69]
	s_setprio 0
	s_barrier
	v_lshl_add_u64 v[144:145], s[76:77], 0, v[178:179]
	s_add_i32 s76, s78, s88
	s_mov_b32 m0, s76
	ds_read_b128 v[172:175], v147 offset:16384
	ds_read_b128 v[180:183], v147 offset:17408
	ds_read_b128 v[184:187], v147 offset:18432
	ds_read_b128 v[188:191], v147 offset:19456
	ds_read_b128 v[192:195], v147 offset:20480
	ds_read_b128 v[196:199], v147 offset:21504
	ds_read_b128 v[200:203], v147 offset:22528
	ds_read_b128 v[210:213], v147 offset:23552
	global_load_lds_dwordx4 v[144:145], off
	v_lshl_add_u64 v[176:177], v[144:145], 0, s[20:21]
	s_add_i32 m0, s76, 0x2000
	s_add_i32 s76, s79, s88
	global_load_lds_dwordx4 v[176:177], off
	v_lshl_add_u64 v[176:177], v[144:145], 0, s[22:23]
	s_mov_b32 m0, s76
	s_nop 0
	global_load_lds_dwordx4 v[176:177], off
	v_lshl_add_u64 v[176:177], v[144:145], 0, s[24:25]
	s_add_i32 m0, s76, 0x2000
	s_nop 0
	global_load_lds_dwordx4 v[176:177], off
	v_lshl_add_u64 v[176:177], s[80:81], 0, v[134:135]
	s_mov_b32 m0, s45
	v_lshl_add_u64 v[208:209], v[176:177], 0, s[20:21]
	global_load_lds_dwordx4 v[176:177], off
	s_mov_b32 m0, s83
	s_nop 0
	global_load_lds_dwordx4 v[208:209], off
	s_cmp_eq_u32 s69, s101
	s_cbranch_scc1 .Lgup_skipw1
	s_waitcnt vmcnt(8)
; #define PG8_STAGE(bufoff, gbase, voff) do { _Pragma("unroll") for (int _i = 0; _i < 2; ++_i) \
;         __builtin_amdgcn_global_load_lds((const unsigned*)((const char*)(gbase) + (size_t)_i * qstep + (voff)[0]), (PG8_LAS unsigned*)(lds + (bufoff) + ldsw + _i * 8192), 16, 0, 0); } while (0)
; #define PG8_LDA(dst, b, h) do { _Pragma("unroll") for (int m = 0; m < 4; ++m) _Pragma("unroll") for (int k = 0; k < 2; ++k) dst[m][k] = *(const PG8_LAS bf16x8*)(lds + PG8_SA(b, h) + aoff + m * 2048 + k * 1024); } while (0)
; #define PG8_LDB(dst, b, h) do { _Pragma("unroll") for (int n = 0; n < 2; ++n) _Pragma("unroll") for (int k = 0; k < 2; ++k) dst[n][k] = *(const PG8_LAS bf16x8*)(lds + PG8_SB(b, h) + boff + n * 2048 + k * 1024); } while (0)
; #define PG8_MMA(ai, bj, At, Bt) do { __builtin_amdgcn_s_setprio(1); _Pragma("unroll") for (int m = 0; m < 4; ++m) _Pragma("unroll") for (int n = 0; n < 2; ++n) _Pragma("unroll") for (int k = 0; k < 2; ++k) \
;         acc[ai][bj][m][n] = __builtin_amdgcn_mfma_f32_16x16x32_bf16(Bt[n][k], At[m][k], acc[ai][bj][m][n], 0, 0, 0); __builtin_amdgcn_s_setprio(0); } while (0)
; #define PG8_WAIT_V89() do { if constexpr (SLIVER) PG8_WAIT_V(9); else PG8_WAIT_V(8); } while (0)
; #define PG8_STAGE_S(b, gbase) do { if constexpr (SLIVER) __builtin_amdgcn_global_load_lds((const unsigned*)((const char*)(gbase) + voffS), (PG8_LAS unsigned*)(lds + STAGE_BYTES + (b) * 2048 + wid * 256), 4, 0, 0); } while (0)
; #define PG8_WAIT_L(n) asm volatile("s_waitcnt lgkmcnt(" #n ")" ::: "memory")
; #define PG8_BAR __builtin_amdgcn_s_barrier()
; #define PG8_SCHED __builtin_amdgcn_sched_barrier(0)
; template <class Epi, class Sched, bool ALIGN_EPI = false, bool SP2 = false, bool SLIVER = false>
; __device__ __forceinline__ void gemm_phase(PG8_LAS unsigned char* lds, const Gemm g, const Sched& S, const Epi& E) {
;     ...
;             PG8_WAIT_V89(); PG8_WAIT_L(0); PG8_BAR; PG8_MMA(1, 0, At, B0); PG8_MMA(1, 1, At, B1); PG8_MMA_S(); PG8_BAR; PG8_SCHED;
;             PG8_LDB(B0, 1, 0); PG8_LDB(B1, 1, 1); PG8_SCHED; PG8_LDA(At, 1, 0); PG8_STAGE(PG8_SA(0, 1), a2 + hstep, voffA); PG8_STAGE_S(0, s2);
;             PG8_WAIT_V89(); PG8_WAIT_L(0); PG8_BAR; PG8_MMA(0, 0, At, B0); PG8_MMA(0, 1, At, B1); PG8_BAR; PG8_SCHED;
.Lgup_skipw1:
	s_waitcnt lgkmcnt(0)
	s_barrier
	s_setprio 1
	s_waitcnt lgkmcnt(0)
	v_mfma_f32_16x16x32_bf16 v[62:65], v[130:133], v[172:175], v[62:65]
	v_mfma_f32_16x16x32_bf16 v[54:57], v[148:151], v[172:175], v[54:57]
	v_mfma_f32_16x16x32_bf16 v[46:49], v[130:133], v[184:187], v[46:49]
	v_mfma_f32_16x16x32_bf16 v[38:41], v[148:151], v[184:187], v[38:41]
	v_mfma_f32_16x16x32_bf16 v[30:33], v[130:133], v[192:195], v[30:33]
	v_mfma_f32_16x16x32_bf16 v[22:25], v[148:151], v[192:195], v[22:25]
	v_mfma_f32_16x16x32_bf16 v[14:17], v[130:133], v[200:203], v[14:17]
	v_mfma_f32_16x16x32_bf16 v[6:9], v[148:151], v[200:203], v[6:9]
	v_mfma_f32_16x16x32_bf16 v[62:65], v[138:141], v[180:183], v[62:65]
	v_mfma_f32_16x16x32_bf16 v[54:57], v[152:155], v[180:183], v[54:57]
	v_mfma_f32_16x16x32_bf16 v[46:49], v[138:141], v[188:191], v[46:49]
	v_mfma_f32_16x16x32_bf16 v[38:41], v[152:155], v[188:191], v[38:41]
	v_mfma_f32_16x16x32_bf16 v[30:33], v[138:141], v[196:199], v[30:33]
	v_mfma_f32_16x16x32_bf16 v[22:25], v[152:155], v[196:199], v[22:25]
	v_mfma_f32_16x16x32_bf16 v[14:17], v[138:141], v[210:213], v[14:17]
	v_mfma_f32_16x16x32_bf16 v[6:9], v[152:155], v[210:213], v[6:9]
	s_setprio 0
	s_setprio 1
	v_mfma_f32_16x16x32_bf16 v[58:61], v[156:159], v[172:175], v[58:61]
	v_mfma_f32_16x16x32_bf16 v[50:53], v[164:167], v[172:175], v[50:53]
	v_mfma_f32_16x16x32_bf16 v[42:45], v[156:159], v[184:187], v[42:45]
	v_mfma_f32_16x16x32_bf16 v[34:37], v[164:167], v[184:187], v[34:37]
	v_mfma_f32_16x16x32_bf16 v[26:29], v[156:159], v[192:195], v[26:29]
	v_mfma_f32_16x16x32_bf16 v[18:21], v[164:167], v[192:195], v[18:21]
	v_mfma_f32_16x16x32_bf16 v[10:13], v[156:159], v[200:203], v[10:13]
	v_mfma_f32_16x16x32_bf16 v[2:5], v[164:167], v[200:203], v[2:5]
	v_mfma_f32_16x16x32_bf16 v[58:61], v[160:163], v[180:183], v[58:61]
	v_mfma_f32_16x16x32_bf16 v[50:53], v[168:171], v[180:183], v[50:53]
	v_mfma_f32_16x16x32_bf16 v[42:45], v[160:163], v[188:191], v[42:45]
	v_mfma_f32_16x16x32_bf16 v[34:37], v[168:171], v[188:191], v[34:37]
	v_mfma_f32_16x16x32_bf16 v[26:29], v[160:163], v[196:199], v[26:29]
	v_mfma_f32_16x16x32_bf16 v[18:21], v[168:171], v[196:199], v[18:21]
	v_mfma_f32_16x16x32_bf16 v[10:13], v[160:163], v[210:213], v[10:13]
	v_mfma_f32_16x16x32_bf16 v[2:5], v[168:171], v[210:213], v[2:5]
	s_setprio 0
	s_barrier
	s_add_i32 s76, 0, 0x18000
	v_add_u32_e32 v142, s76, v143
	s_add_i32 s77, 0, 0x1c000
	ds_read_b128 v[130:133], v142
	ds_read_b128 v[138:141], v142 offset:1024
	ds_read_b128 v[148:151], v142 offset:2048
	ds_read_b128 v[152:155], v142 offset:3072
	v_add_u32_e32 v142, s77, v143
	ds_read_b128 v[156:159], v142
	ds_read_b128 v[160:163], v142 offset:1024
	ds_read_b128 v[164:167], v142 offset:2048
	ds_read_b128 v[168:171], v142 offset:3072
	s_mov_b32 m0, s90
	v_lshl_add_u64 v[208:209], v[176:177], 0, s[22:23]
	ds_read_b128 v[172:175], v147 offset:32768
	ds_read_b128 v[180:183], v147 offset:33792
	ds_read_b128 v[184:187], v147 offset:34816
	ds_read_b128 v[188:191], v147 offset:35840
	ds_read_b128 v[192:195], v147 offset:36864
	ds_read_b128 v[196:199], v147 offset:37888
	ds_read_b128 v[200:203], v147 offset:38912
	ds_read_b128 v[210:213], v147 offset:39936
	global_load_lds_dwordx4 v[208:209], off
	v_lshl_add_u64 v[208:209], v[176:177], 0, s[24:25]
	s_mov_b32 m0, s91
	s_nop 0
	global_load_lds_dwordx4 v[208:209], off
	s_waitcnt vmcnt(8)
	s_waitcnt lgkmcnt(0)
	s_barrier
	s_setprio 1
	s_waitcnt lgkmcnt(0)
	v_mfma_f32_16x16x32_bf16 v[126:129], v[130:133], v[172:175], v[126:129]
	v_mfma_f32_16x16x32_bf16 v[118:121], v[148:151], v[172:175], v[118:121]
	v_mfma_f32_16x16x32_bf16 v[110:113], v[130:133], v[184:187], v[110:113]
	v_mfma_f32_16x16x32_bf16 v[102:105], v[148:151], v[184:187], v[102:105]
	v_mfma_f32_16x16x32_bf16 v[94:97], v[130:133], v[192:195], v[94:97]
	v_mfma_f32_16x16x32_bf16 v[86:89], v[148:151], v[192:195], v[86:89]
	v_mfma_f32_16x16x32_bf16 v[78:81], v[130:133], v[200:203], v[78:81]
	v_mfma_f32_16x16x32_bf16 v[70:73], v[148:151], v[200:203], v[70:73]
	v_mfma_f32_16x16x32_bf16 v[126:129], v[138:141], v[180:183], v[126:129]
	v_mfma_f32_16x16x32_bf16 v[118:121], v[152:155], v[180:183], v[118:121]
	v_mfma_f32_16x16x32_bf16 v[110:113], v[138:141], v[188:191], v[110:113]
	v_mfma_f32_16x16x32_bf16 v[102:105], v[152:155], v[188:191], v[102:105]
	v_mfma_f32_16x16x32_bf16 v[94:97], v[138:141], v[196:199], v[94:97]
	v_mfma_f32_16x16x32_bf16 v[86:89], v[152:155], v[196:199], v[86:89]
	v_mfma_f32_16x16x32_bf16 v[78:81], v[138:141], v[210:213], v[78:81]
	v_mfma_f32_16x16x32_bf16 v[70:73], v[152:155], v[210:213], v[70:73]
	s_setprio 0
	s_setprio 1
	v_mfma_f32_16x16x32_bf16 v[122:125], v[156:159], v[172:175], v[122:125]
	v_mfma_f32_16x16x32_bf16 v[114:117], v[164:167], v[172:175], v[114:117]
	v_mfma_f32_16x16x32_bf16 v[106:109], v[156:159], v[184:187], v[106:109]
	v_mfma_f32_16x16x32_bf16 v[98:101], v[164:167], v[184:187], v[98:101]
	v_mfma_f32_16x16x32_bf16 v[90:93], v[156:159], v[192:195], v[90:93]
	v_mfma_f32_16x16x32_bf16 v[82:85], v[164:167], v[192:195], v[82:85]
	v_mfma_f32_16x16x32_bf16 v[74:77], v[156:159], v[200:203], v[74:77]
	v_mfma_f32_16x16x32_bf16 v[66:69], v[164:167], v[200:203], v[66:69]
	v_mfma_f32_16x16x32_bf16 v[122:125], v[160:163], v[180:183], v[122:125]
	v_mfma_f32_16x16x32_bf16 v[114:117], v[168:171], v[180:183], v[114:117]
	v_mfma_f32_16x16x32_bf16 v[106:109], v[160:163], v[188:191], v[106:109]
	v_mfma_f32_16x16x32_bf16 v[98:101], v[168:171], v[188:191], v[98:101]
	v_mfma_f32_16x16x32_bf16 v[90:93], v[160:163], v[196:199], v[90:93]
	v_mfma_f32_16x16x32_bf16 v[82:85], v[168:171], v[196:199], v[82:85]
	v_mfma_f32_16x16x32_bf16 v[74:77], v[160:163], v[210:213], v[74:77]
	v_mfma_f32_16x16x32_bf16 v[66:69], v[168:171], v[210:213], v[66:69]
	s_setprio 0
	s_barrier
; #define PG8_SB(B) __builtin_amdgcn_rcpf(1.f + expneg(B))
; #define PG8_SB(B) __builtin_amdgcn_rcpf(1.f + expneg(B))
; #define PG8_STAGE(bufoff, gbase, voff) do { _Pragma("unroll") for (int _i = 0; _i < 2; ++_i) \
;         __builtin_amdgcn_global_load_lds((const unsigned*)((const char*)(gbase) + (size_t)_i * qstep + (voff)[0]), (PG8_LAS unsigned*)(lds + (bufoff) + ldsw + _i * 8192), 16, 0, 0); } while (0)
; #define PG8_LDA(dst, b, h) do { _Pragma("unroll") for (int m = 0; m < 4; ++m) _Pragma("unroll") for (int k = 0; k < 2; ++k) dst[m][k] = *(const PG8_LAS bf16x8*)(lds + PG8_SA(b, h) + aoff + m * 2048 + k * 1024); } while (0)
; #define PG8_MMA(ai, bj, At, Bt) do { __builtin_amdgcn_s_setprio(1); _Pragma("unroll") for (int m = 0; m < 4; ++m) _Pragma("unroll") for (int n = 0; n < 2; ++n) _Pragma("unroll") for (int k = 0; k < 2; ++k) \
;         acc[ai][bj][m][n] = __builtin_amdgcn_mfma_f32_16x16x32_bf16(Bt[n][k], At[m][k], acc[ai][bj][m][n], 0, 0, 0); __builtin_amdgcn_s_setprio(0); } while (0)
; #define PG8_WAIT_V89() do { if constexpr (SLIVER) PG8_WAIT_V(9); else PG8_WAIT_V(8); } while (0)
; #define PG8_LDS_S(b) do { if constexpr (SLIVER) { Sf[0] = *(const PG8_LAS bf16x8*)(lds + STAGE_BYTES + (b) * 2048 + soff0); Sf[1] = *(const PG8_LAS bf16x8*)(lds + STAGE_BYTES + (b) * 2048 + (soff0 ^ 64)); } } while (0)
; #define PG8_WAIT_L(n) asm volatile("s_waitcnt lgkmcnt(" #n ")" ::: "memory")
; #define PG8_BAR __builtin_amdgcn_s_barrier()
;     __device__ __forceinline__ void operator()(const f32x4 (&acc)[2][2][4][2], const Unit& u, int wr, int wc, int fr, int fq) const {
;         const int rowt = u.pm * BM + wr * 64 + fr, col0 = u.pn * HALF + wc * 32 + 8 * fq;
;         float rsv[2][4];
; #pragma unroll
;         for (int ai = 0; ai < 2; ++ai)
; #pragma unroll
;             for (int m = 0; m < 4; ++m) rsv[ai][m] = row_rstd(ss, rowt + ai * HALF + m * 16);
; template <class Epi, class Sched, bool ALIGN_EPI = false, bool SP2 = false, bool SLIVER = false>
; __device__ __forceinline__ void gemm_phase(PG8_LAS unsigned char* lds, const Gemm g, const Sched& S, const Epi& E) {
;     ...
;             PG8_LDA(At, 1, 1); PG8_LDS_S(1); PG8_STAGE(PG8_SB(1, 0), b3, voffB); PG8_STAGE(PG8_SB(1, 1), b3 + hstep, voffB); PG8_STAGE(PG8_SA(1, 0), a3, voffA);
;             PG8_WAIT_V89(); PG8_WAIT_L(0); PG8_BAR; PG8_MMA(1, 0, At, B0); PG8_MMA(1, 1, At, B1); PG8_MMA_S(); PG8_BAR; PG8_SCHED;
	s_add_i32 s76, s76, s88
	v_lshl_add_u64 v[208:209], v[144:145], 0, s[26:27]
	s_mov_b32 m0, s76
	ds_read_b128 v[172:175], v147 offset:49152
	ds_read_b128 v[180:183], v147 offset:50176
	ds_read_b128 v[184:187], v147 offset:51200
	ds_read_b128 v[188:191], v147 offset:52224
	ds_read_b128 v[192:195], v147 offset:53248
	ds_read_b128 v[196:199], v147 offset:54272
	ds_read_b128 v[200:203], v147 offset:55296
	ds_read_b128 v[210:213], v147 offset:56320
	global_load_lds_dwordx4 v[208:209], off
	v_lshl_add_u64 v[208:209], v[144:145], 0, s[28:29]
	s_add_i32 m0, s76, 0x2000
	s_add_i32 s76, s77, s88
	global_load_lds_dwordx4 v[208:209], off
	v_lshl_add_u64 v[208:209], v[144:145], 0, s[30:31]
	s_mov_b32 m0, s76
	v_lshl_add_u64 v[144:145], v[144:145], 0, s[34:35]
	global_load_lds_dwordx4 v[208:209], off
	s_add_i32 m0, s76, 0x2000
	s_nop 0
	global_load_lds_dwordx4 v[144:145], off
	v_lshl_add_u64 v[144:145], v[176:177], 0, s[26:27]
	s_mov_b32 m0, s93
	s_nop 0
	global_load_lds_dwordx4 v[144:145], off
	v_lshl_add_u64 v[144:145], v[176:177], 0, s[28:29]
	s_mov_b32 m0, s94
	s_nop 0
	global_load_lds_dwordx4 v[144:145], off
	s_waitcnt vmcnt(8)
	s_waitcnt lgkmcnt(0)
	s_barrier
	s_setprio 1
	s_waitcnt lgkmcnt(0)
	v_mfma_f32_16x16x32_bf16 v[62:65], v[130:133], v[172:175], v[62:65]
	v_mfma_f32_16x16x32_bf16 v[54:57], v[148:151], v[172:175], v[54:57]
	v_mfma_f32_16x16x32_bf16 v[46:49], v[130:133], v[184:187], v[46:49]
	v_mfma_f32_16x16x32_bf16 v[38:41], v[148:151], v[184:187], v[38:41]
	v_mfma_f32_16x16x32_bf16 v[30:33], v[130:133], v[192:195], v[30:33]
	v_mfma_f32_16x16x32_bf16 v[22:25], v[148:151], v[192:195], v[22:25]
	v_mfma_f32_16x16x32_bf16 v[14:17], v[130:133], v[200:203], v[14:17]
	v_mfma_f32_16x16x32_bf16 v[6:9], v[148:151], v[200:203], v[6:9]
	v_mfma_f32_16x16x32_bf16 v[62:65], v[138:141], v[180:183], v[62:65]
	v_mfma_f32_16x16x32_bf16 v[54:57], v[152:155], v[180:183], v[54:57]
	v_mfma_f32_16x16x32_bf16 v[46:49], v[138:141], v[188:191], v[46:49]
	v_mfma_f32_16x16x32_bf16 v[38:41], v[152:155], v[188:191], v[38:41]
	v_mfma_f32_16x16x32_bf16 v[30:33], v[138:141], v[196:199], v[30:33]
	v_mfma_f32_16x16x32_bf16 v[22:25], v[152:155], v[196:199], v[22:25]
	v_mfma_f32_16x16x32_bf16 v[14:17], v[138:141], v[210:213], v[14:17]
	v_mfma_f32_16x16x32_bf16 v[6:9], v[152:155], v[210:213], v[6:9]
	s_setprio 0
	s_setprio 1
	v_mfma_f32_16x16x32_bf16 v[58:61], v[156:159], v[172:175], v[58:61]
	v_mfma_f32_16x16x32_bf16 v[50:53], v[164:167], v[172:175], v[50:53]
	v_mfma_f32_16x16x32_bf16 v[42:45], v[156:159], v[184:187], v[42:45]
	v_mfma_f32_16x16x32_bf16 v[34:37], v[164:167], v[184:187], v[34:37]
	v_mfma_f32_16x16x32_bf16 v[26:29], v[156:159], v[192:195], v[26:29]
	v_mfma_f32_16x16x32_bf16 v[18:21], v[164:167], v[192:195], v[18:21]
	v_mfma_f32_16x16x32_bf16 v[10:13], v[156:159], v[200:203], v[10:13]
	v_mfma_f32_16x16x32_bf16 v[2:5], v[164:167], v[200:203], v[2:5]
	v_mfma_f32_16x16x32_bf16 v[58:61], v[160:163], v[180:183], v[58:61]
	v_mfma_f32_16x16x32_bf16 v[50:53], v[168:171], v[180:183], v[50:53]
	v_mfma_f32_16x16x32_bf16 v[42:45], v[160:163], v[188:191], v[42:45]
	v_mfma_f32_16x16x32_bf16 v[34:37], v[168:171], v[188:191], v[34:37]
	v_mfma_f32_16x16x32_bf16 v[26:29], v[160:163], v[196:199], v[26:29]
	v_mfma_f32_16x16x32_bf16 v[18:21], v[168:171], v[196:199], v[18:21]
	v_mfma_f32_16x16x32_bf16 v[10:13], v[160:163], v[210:213], v[10:13]
	v_mfma_f32_16x16x32_bf16 v[2:5], v[168:171], v[210:213], v[2:5]
	s_setprio 0
	s_barrier
	s_add_i32 s69, s69, 2
	s_add_u32 s62, s62, 0x100
	s_addc_u32 s63, s63, 0
	s_add_u32 s67, s67, 0x100
	s_addc_u32 s68, s68, 0
	s_cmp_gt_u32 s69, 29
	s_cbranch_scc0 .LBB0_705
	s_and_b64 vcc, exec, s[42:43]
	s_cbranch_vccz .LBB0_708
	s_barrier
.LBB0_708:
	s_lshl_b32 s3, s82, 8
	v_mov_b32_e32 v130, v0
	s_add_i32 s3, s3, s10
	s_lshl_b32 s2, s2, 7
	v_and_or_b32 v164, v130, 15, s3
	v_ashrrev_i32_e32 v165, 31, v164
	v_lshrrev_b32_e32 v151, 1, v130
	v_lshl_add_u64 v[210:211], v[164:165], 4, s[40:41]
	global_load_dwordx4 v[210:213], v[210:211], off
	v_or_b32_e32 v160, 16, v164
	v_ashrrev_i32_e32 v161, 31, v160
	v_or_b32_e32 v156, 32, v164
	v_ashrrev_i32_e32 v157, 31, v156
	v_or_b32_e32 v152, 48, v164
	v_ashrrev_i32_e32 v153, 31, v152
	v_add_u32_e32 v148, 0x80, v164
	v_ashrrev_i32_e32 v149, 31, v148
	v_add_u32_e32 v144, 0x90, v164
	v_ashrrev_i32_e32 v145, 31, v144
	v_lshl_add_u64 v[180:181], v[160:161], 4, s[40:41]
	global_load_dwordx4 v[180:183], v[180:181], off
	v_lshl_add_u64 v[184:185], v[156:157], 4, s[40:41]
	global_load_dwordx4 v[184:187], v[184:185], off
	v_lshl_add_u64 v[188:189], v[152:153], 4, s[40:41]
	global_load_dwordx4 v[188:191], v[188:189], off
	v_lshl_add_u64 v[192:193], v[148:149], 4, s[40:41]
	global_load_dwordx4 v[192:195], v[192:193], off
	v_lshl_add_u64 v[196:197], v[144:145], 4, s[40:41]
	global_load_dwordx4 v[196:199], v[196:197], off
	v_add_u32_e32 v214, 0xa0, v164
	v_ashrrev_i32_e32 v215, 31, v214
	v_add_u32_e32 v216, 0xb0, v164
	v_ashrrev_i32_e32 v217, 31, v216
	v_lshl_add_u64 v[200:201], v[214:215], 4, s[40:41]
	global_load_dwordx4 v[200:203], v[200:201], off
	v_lshl_add_u64 v[130:131], v[216:217], 4, s[40:41]
	global_load_dwordx4 v[130:133], v[130:131], off
	s_movk_i32 s49, 0x2c00
	s_mov_b64 s[62:63], -1
	s_andn2_b64 vcc, exec, s[38:39]
	v_readlane_b32 s79, v254, 35
	s_movk_i32 s77, 0x70
	s_mov_b64 s[68:69], 0x4000c00
	s_waitcnt vmcnt(7)
	v_lshlrev_b32_e32 v139, 16, v212
	v_lshlrev_b32_e32 v138, 16, v210
	v_and_b32_e32 v141, 0xffff0000, v212
	v_and_b32_e32 v140, 0xffff0000, v210
	v_pk_add_f32 v[138:139], v[138:139], v[140:141]
	v_lshlrev_b32_e32 v141, 16, v213
	v_lshlrev_b32_e32 v140, 16, v211
	v_and_b32_e32 v213, 0xffff0000, v213
	v_and_b32_e32 v212, 0xffff0000, v211
	v_pk_add_f32 v[210:211], v[140:141], v[212:213]
	s_nop 0
	v_pk_add_f32 v[210:211], v[138:139], v[210:211]
	s_nop 0
	v_add_f32_e32 v210, v210, v211
	v_fmamk_f32 v210, v210, 0x3a000000, v1
	v_rsq_f32_e32 v166, v210
	s_waitcnt vmcnt(6)
; __device__ __forceinline__ float expneg(float g) { return ex2(fminf(-g * 1.4426950408889634f, 80.f)); }
;     __device__ __forceinline__ void operator()(const f32x4 (&acc)[2][2][4][2], const Unit& u, int wr, int wc, int fr, int fq) const {
;     ...
; #pragma unroll
;         for (int ai = 0; ai < 2; ++ai)
; #pragma unroll
;             for (int m = 0; m < 4; ++m) rsv[ai][m] = row_rstd(ss, rowt + ai * HALF + m * 16);
; #pragma unroll
;         for (int ai = 0; ai < 2; ++ai)
; #pragma unroll
;             for (int m = 0; m < 4; ++m) { f32x4 v[2]; const float rs = rsv[ai][m];
; #pragma unroll
;                 for (int n = 0; n < 2; ++n)
; #pragma unroll
;                     for (int i = 0; i < 4; ++i) { const float g = acc[ai][0][m][n][i] * rs; v[n][i] = g * __builtin_amdgcn_rcpf(1.f + expneg(g)) * (acc[ai][1][m][n][i] * rs); }
	v_lshlrev_b32_e32 v139, 16, v182
	v_lshlrev_b32_e32 v138, 16, v180
	v_and_b32_e32 v141, 0xffff0000, v182
	v_and_b32_e32 v140, 0xffff0000, v180
	v_pk_add_f32 v[138:139], v[138:139], v[140:141]
	v_lshlrev_b32_e32 v141, 16, v183
	v_lshlrev_b32_e32 v140, 16, v181
	v_and_b32_e32 v183, 0xffff0000, v183
	v_and_b32_e32 v182, 0xffff0000, v181
	v_pk_add_f32 v[180:181], v[140:141], v[182:183]
	s_nop 0
	v_pk_add_f32 v[180:181], v[138:139], v[180:181]
	s_nop 0
	v_add_f32_e32 v180, v180, v181
	v_fmamk_f32 v180, v180, 0x3a000000, v1
	v_rsq_f32_e32 v162, v180
	s_waitcnt vmcnt(5)
	v_lshlrev_b32_e32 v139, 16, v186
	v_lshlrev_b32_e32 v138, 16, v184
	v_and_b32_e32 v141, 0xffff0000, v186
	v_and_b32_e32 v140, 0xffff0000, v184
	v_pk_add_f32 v[138:139], v[138:139], v[140:141]
	v_lshlrev_b32_e32 v141, 16, v187
	v_lshlrev_b32_e32 v140, 16, v185
	v_and_b32_e32 v187, 0xffff0000, v187
	v_and_b32_e32 v186, 0xffff0000, v185
	v_pk_add_f32 v[184:185], v[140:141], v[186:187]
	s_nop 0
	v_pk_add_f32 v[184:185], v[138:139], v[184:185]
	s_nop 0
	v_add_f32_e32 v184, v184, v185
	v_fmamk_f32 v184, v184, 0x3a000000, v1
	v_rsq_f32_e32 v158, v184
	s_waitcnt vmcnt(4)
	v_lshlrev_b32_e32 v139, 16, v190
	v_lshlrev_b32_e32 v138, 16, v188
	v_and_b32_e32 v141, 0xffff0000, v190
	v_and_b32_e32 v140, 0xffff0000, v188
	v_pk_add_f32 v[138:139], v[138:139], v[140:141]
	v_lshlrev_b32_e32 v141, 16, v191
	v_lshlrev_b32_e32 v140, 16, v189
	v_and_b32_e32 v191, 0xffff0000, v191
	v_and_b32_e32 v190, 0xffff0000, v189
	v_pk_add_f32 v[188:189], v[140:141], v[190:191]
	s_nop 0
	v_pk_add_f32 v[188:189], v[138:139], v[188:189]
	s_nop 0
	v_add_f32_e32 v188, v188, v189
	v_fmamk_f32 v188, v188, 0x3a000000, v1
	v_rsq_f32_e32 v154, v188
	s_waitcnt vmcnt(3)
	v_lshlrev_b32_e32 v139, 16, v194
	v_lshlrev_b32_e32 v138, 16, v192
	v_and_b32_e32 v141, 0xffff0000, v194
	v_and_b32_e32 v140, 0xffff0000, v192
	v_pk_add_f32 v[138:139], v[138:139], v[140:141]
	v_lshlrev_b32_e32 v141, 16, v195
	v_lshlrev_b32_e32 v140, 16, v193
	v_and_b32_e32 v195, 0xffff0000, v195
	v_and_b32_e32 v194, 0xffff0000, v193
	v_pk_add_f32 v[192:193], v[140:141], v[194:195]
	s_nop 0
	v_pk_add_f32 v[192:193], v[138:139], v[192:193]
	s_nop 0
	v_add_f32_e32 v192, v192, v193
	v_fmamk_f32 v192, v192, 0x3a000000, v1
	v_rsq_f32_e32 v150, v192
	s_waitcnt vmcnt(2)
	v_lshlrev_b32_e32 v139, 16, v198
	v_lshlrev_b32_e32 v138, 16, v196
	v_and_b32_e32 v141, 0xffff0000, v198
	v_and_b32_e32 v140, 0xffff0000, v196
	v_pk_add_f32 v[138:139], v[138:139], v[140:141]
	v_lshlrev_b32_e32 v141, 16, v199
	v_lshlrev_b32_e32 v140, 16, v197
	v_and_b32_e32 v199, 0xffff0000, v199
	v_and_b32_e32 v198, 0xffff0000, v197
	v_pk_add_f32 v[196:197], v[140:141], v[198:199]
	v_add_u32_e32 v140, 0xa0, v164
	v_pk_add_f32 v[196:197], v[138:139], v[196:197]
	v_ashrrev_i32_e32 v141, 31, v140
	v_add_f32_e32 v196, v196, v197
	v_fmamk_f32 v196, v196, 0x3a000000, v1
	v_rsq_f32_e32 v146, v196
	s_waitcnt vmcnt(1)
	v_lshlrev_b32_e32 v139, 16, v202
	v_lshlrev_b32_e32 v138, 16, v200
	v_and_b32_e32 v169, 0xffff0000, v202
	v_and_b32_e32 v168, 0xffff0000, v200
	v_pk_add_f32 v[138:139], v[138:139], v[168:169]
	v_lshlrev_b32_e32 v169, 16, v203
	v_lshlrev_b32_e32 v168, 16, v201
	v_and_b32_e32 v203, 0xffff0000, v203
	v_and_b32_e32 v202, 0xffff0000, v201
	v_pk_add_f32 v[200:201], v[168:169], v[202:203]
	s_nop 0
	v_pk_add_f32 v[200:201], v[138:139], v[200:201]
	v_add_u32_e32 v138, 0xb0, v164
	v_add_f32_e32 v200, v200, v201
	v_fmamk_f32 v200, v200, 0x3a000000, v1
	v_ashrrev_i32_e32 v139, 31, v138
	v_rsq_f32_e32 v142, v200
	s_waitcnt vmcnt(0)
	v_lshlrev_b32_e32 v169, 16, v132
	v_lshlrev_b32_e32 v168, 16, v130
	v_and_b32_e32 v171, 0xffff0000, v132
	v_and_b32_e32 v170, 0xffff0000, v130
	v_pk_add_f32 v[168:169], v[168:169], v[170:171]
	v_lshlrev_b32_e32 v171, 16, v133
	v_lshlrev_b32_e32 v170, 16, v131
	v_and_b32_e32 v133, 0xffff0000, v133
	v_and_b32_e32 v132, 0xffff0000, v131
	v_pk_add_f32 v[130:131], v[170:171], v[132:133]
	s_nop 0
	v_pk_add_f32 v[130:131], v[168:169], v[130:131]
	v_mov_b32_e32 v168, v122
	v_mov_b32_e32 v169, v126
	v_pk_mul_f32 v[168:169], v[168:169], v[166:167] op_sel_hi:[1,0]
	v_add_f32_e32 v130, v130, v131
	v_mul_f32_e32 v122, 0xbfb8aa3b, v169
	v_min_f32_e32 v122, 0x42a00000, v122
	v_exp_f32_e32 v122, v122
	v_and_or_b32 v131, v151, 24, s2
	v_mov_b32_e32 v126, v123
	v_or_b32_e32 v132, s92, v131
	v_add_f32_e32 v122, 1.0, v122
	v_rcp_f32_e32 v122, v122
	v_ashrrev_i32_e32 v133, 31, v132
	v_fmamk_f32 v130, v130, 0x3a000000, v1
	v_rsq_f32_e32 v130, v130
	v_mul_f32_e32 v122, v169, v122
	v_mul_f32_e32 v131, v168, v122
	v_pk_mul_f32 v[122:123], v[126:127], v[166:167] op_sel_hi:[1,0]
	s_nop 0
	v_mul_f32_e32 v126, 0xbfb8aa3b, v123
	v_min_f32_e32 v126, 0x42a00000, v126
	v_exp_f32_e32 v126, v126
	s_nop 0
	v_add_f32_e32 v126, 1.0, v126
	v_rcp_f32_e32 v126, v126
	s_nop 0
	v_mul_f32_e32 v123, v123, v126
	v_mul_f32_e32 v126, v122, v123
	v_mov_b32_e32 v122, v124
	v_mov_b32_e32 v123, v128
	v_pk_mul_f32 v[122:123], v[122:123], v[166:167] op_sel_hi:[1,0]
	v_mov_b32_e32 v128, v125
	v_mul_f32_e32 v124, 0xbfb8aa3b, v123
	v_min_f32_e32 v124, 0x42a00000, v124
	v_exp_f32_e32 v124, v124
	s_nop 0
	v_add_f32_e32 v124, 1.0, v124
	v_rcp_f32_e32 v124, v124
	s_nop 0
	v_mul_f32_e32 v123, v123, v124
	v_mul_f32_e32 v124, v122, v123
	v_pk_mul_f32 v[122:123], v[128:129], v[166:167] op_sel_hi:[1,0]
	s_nop 0
	v_mul_f32_e32 v125, 0xbfb8aa3b, v123
	v_min_f32_e32 v125, 0x42a00000, v125
	v_exp_f32_e32 v125, v125
	s_nop 0
	v_add_f32_e32 v125, 1.0, v125
	v_rcp_f32_e32 v125, v125
	s_nop 0
	v_mul_f32_e32 v123, v123, v125
	v_mul_f32_e32 v125, v122, v123
	v_mov_b32_e32 v122, v114
	v_mov_b32_e32 v123, v118
	v_pk_mul_f32 v[122:123], v[122:123], v[166:167] op_sel_hi:[1,0]
; __device__ __forceinline__ u32x4 pack8(const f32x4& a, const f32x4& b) { u32x4 w; w.x = cvt_pk_bf16(a[0], a[1]); w.y = cvt_pk_bf16(a[2], a[3]); w.z = cvt_pk_bf16(b[0], b[1]); w.w = cvt_pk_bf16(b[2], b[3]); return w; }
; __device__ __forceinline__ float expneg(float g) { return ex2(fminf(-g * 1.4426950408889634f, 80.f)); }
;     __device__ __forceinline__ void operator()(const f32x4 (&acc)[2][2][4][2], const Unit& u, int wr, int wc, int fr, int fq) const {
;     ...
;         for (int ai = 0; ai < 2; ++ai)
; #pragma unroll
;             for (int m = 0; m < 4; ++m) { f32x4 v[2]; const float rs = rsv[ai][m];
; #pragma unroll
;                 for (int n = 0; n < 2; ++n)
; #pragma unroll
;                     for (int i = 0; i < 4; ++i) { const float g = acc[ai][0][m][n][i] * rs; v[n][i] = g * __builtin_amdgcn_rcpf(1.f + expneg(g)) * (acc[ai][1][m][n][i] * rs); }
;                 *(u32x4*)(act + (size_t)(rowt + ai * HALF + m * 16) * 5632 + col0) = pack8(v[0], v[1]); }
	v_mov_b32_e32 v118, v115
	v_mul_f32_e32 v114, 0xbfb8aa3b, v123
	v_min_f32_e32 v114, 0x42a00000, v114
	v_exp_f32_e32 v114, v114
	s_nop 0
	v_add_f32_e32 v114, 1.0, v114
	v_rcp_f32_e32 v114, v114
	s_nop 0
	v_mul_f32_e32 v114, v123, v114
	v_mul_f32_e32 v122, v122, v114
	v_pk_mul_f32 v[114:115], v[118:119], v[166:167] op_sel_hi:[1,0]
	s_nop 0
	v_mul_f32_e32 v118, 0xbfb8aa3b, v115
	v_min_f32_e32 v118, 0x42a00000, v118
	v_exp_f32_e32 v118, v118
	s_nop 0
	v_add_f32_e32 v118, 1.0, v118
	v_rcp_f32_e32 v118, v118
	s_nop 0
	v_mul_f32_e32 v115, v115, v118
	v_mul_f32_e32 v123, v114, v115
	v_mov_b32_e32 v114, v116
	v_mov_b32_e32 v115, v120
	v_pk_mul_f32 v[114:115], v[114:115], v[166:167] op_sel_hi:[1,0]
	v_mov_b32_e32 v120, v117
	v_mul_f32_e32 v116, 0xbfb8aa3b, v115
	v_min_f32_e32 v116, 0x42a00000, v116
	v_exp_f32_e32 v116, v116
	v_cvt_pk_bf16_f32 v118, v131, v126
	v_cvt_pk_bf16_f32 v119, v124, v125
	s_nop 0
	v_add_f32_e32 v116, 1.0, v116
	v_rcp_f32_e32 v116, v116
	s_nop 0
	v_mul_f32_e32 v115, v115, v116
	v_mul_f32_e32 v116, v114, v115
	v_pk_mul_f32 v[114:115], v[120:121], v[166:167] op_sel_hi:[1,0]
	v_cvt_pk_bf16_f32 v120, v122, v123
	s_nop 0
	v_mul_f32_e32 v117, 0xbfb8aa3b, v115
	v_min_f32_e32 v117, 0x42a00000, v117
	v_exp_f32_e32 v117, v117
	s_nop 0
	v_add_f32_e32 v117, 1.0, v117
	v_rcp_f32_e32 v117, v117
	s_nop 0
	v_mul_f32_e32 v115, v115, v117
	v_mul_f32_e32 v114, v114, v115
	v_cvt_pk_bf16_f32 v121, v116, v114
	v_mov_b64_e32 v[114:115], s[18:19]
	v_mad_i64_i32 v[122:123], s[2:3], v164, s49, v[114:115]
	v_lshlrev_b64 v[116:117], 1, v[132:133]
	v_lshl_add_u64 v[122:123], v[122:123], 0, v[116:117]
	global_store_dwordx4 v[122:123], v[118:121], off
	s_nop 1
	v_mov_b32_e32 v118, v106
	v_mov_b32_e32 v119, v110
	v_pk_mul_f32 v[118:119], v[118:119], v[162:163] op_sel_hi:[1,0]
	v_mov_b32_e32 v110, v107
	v_mul_f32_e32 v106, 0xbfb8aa3b, v119
	v_min_f32_e32 v106, 0x42a00000, v106
	v_exp_f32_e32 v106, v106
	s_nop 0
	v_add_f32_e32 v106, 1.0, v106
	v_rcp_f32_e32 v106, v106
	s_nop 0
	v_mul_f32_e32 v106, v119, v106
	v_mul_f32_e32 v118, v118, v106
	v_pk_mul_f32 v[106:107], v[110:111], v[162:163] op_sel_hi:[1,0]
	s_nop 0
	v_mul_f32_e32 v110, 0xbfb8aa3b, v107
	v_min_f32_e32 v110, 0x42a00000, v110
	v_exp_f32_e32 v110, v110
	s_nop 0
	v_add_f32_e32 v110, 1.0, v110
	v_rcp_f32_e32 v110, v110
	s_nop 0
	v_mul_f32_e32 v107, v107, v110
	v_mul_f32_e32 v110, v106, v107
	v_mov_b32_e32 v106, v108
	v_mov_b32_e32 v107, v112
	v_pk_mul_f32 v[106:107], v[106:107], v[162:163] op_sel_hi:[1,0]
	v_mov_b32_e32 v112, v109
	v_mul_f32_e32 v108, 0xbfb8aa3b, v107
	v_min_f32_e32 v108, 0x42a00000, v108
	v_exp_f32_e32 v108, v108
	s_nop 0
	v_add_f32_e32 v108, 1.0, v108
	v_rcp_f32_e32 v108, v108
	s_nop 0
	v_mul_f32_e32 v107, v107, v108
	v_mul_f32_e32 v108, v106, v107
	v_pk_mul_f32 v[106:107], v[112:113], v[162:163] op_sel_hi:[1,0]
	s_nop 0
	v_mul_f32_e32 v109, 0xbfb8aa3b, v107
	v_min_f32_e32 v109, 0x42a00000, v109
	v_exp_f32_e32 v109, v109
	s_nop 0
	v_add_f32_e32 v109, 1.0, v109
	v_rcp_f32_e32 v109, v109
	s_nop 0
	v_mul_f32_e32 v107, v107, v109
	v_mul_f32_e32 v109, v106, v107
	v_mov_b32_e32 v106, v98
	v_mov_b32_e32 v107, v102
	v_pk_mul_f32 v[106:107], v[106:107], v[162:163] op_sel_hi:[1,0]
	v_mov_b32_e32 v102, v99
	v_mul_f32_e32 v98, 0xbfb8aa3b, v107
	v_min_f32_e32 v98, 0x42a00000, v98
	v_exp_f32_e32 v98, v98
	s_nop 0
	v_add_f32_e32 v98, 1.0, v98
	v_rcp_f32_e32 v98, v98
	s_nop 0
	v_mul_f32_e32 v98, v107, v98
	v_mul_f32_e32 v106, v106, v98
	v_pk_mul_f32 v[98:99], v[102:103], v[162:163] op_sel_hi:[1,0]
	s_nop 0
	v_mul_f32_e32 v102, 0xbfb8aa3b, v99
	v_min_f32_e32 v102, 0x42a00000, v102
	v_exp_f32_e32 v102, v102
	s_nop 0
	v_add_f32_e32 v102, 1.0, v102
	v_rcp_f32_e32 v102, v102
	s_nop 0
	v_mul_f32_e32 v99, v99, v102
	v_mul_f32_e32 v102, v98, v99
	v_mov_b32_e32 v98, v100
	v_mov_b32_e32 v99, v104
	v_pk_mul_f32 v[98:99], v[98:99], v[162:163] op_sel_hi:[1,0]
	v_mov_b32_e32 v104, v101
	v_mul_f32_e32 v100, 0xbfb8aa3b, v99
	v_min_f32_e32 v100, 0x42a00000, v100
	v_exp_f32_e32 v100, v100
	s_nop 0
	v_add_f32_e32 v100, 1.0, v100
	v_rcp_f32_e32 v100, v100
	s_nop 0
	v_mul_f32_e32 v99, v99, v100
	v_mul_f32_e32 v103, v98, v99
	v_pk_mul_f32 v[98:99], v[104:105], v[162:163] op_sel_hi:[1,0]
	s_nop 0
	v_mul_f32_e32 v100, 0xbfb8aa3b, v99
	v_min_f32_e32 v100, 0x42a00000, v100
	v_exp_f32_e32 v100, v100
	s_nop 0
	v_add_f32_e32 v100, 1.0, v100
	v_rcp_f32_e32 v100, v100
	s_nop 0
	v_mul_f32_e32 v99, v99, v100
	v_mul_f32_e32 v101, v98, v99
	v_cvt_pk_bf16_f32 v98, v118, v110
	v_cvt_pk_bf16_f32 v99, v108, v109
	v_cvt_pk_bf16_f32 v100, v106, v102
	v_cvt_pk_bf16_f32 v101, v103, v101
	v_mad_i64_i32 v[102:103], s[2:3], v160, s49, v[114:115]
	v_lshl_add_u64 v[102:103], v[102:103], 0, v[116:117]
	global_store_dwordx4 v[102:103], v[98:101], off
	s_nop 1
	v_mov_b32_e32 v98, v90
	v_mov_b32_e32 v99, v94
	v_pk_mul_f32 v[98:99], v[98:99], v[158:159] op_sel_hi:[1,0]
	v_mov_b32_e32 v94, v91
	v_mul_f32_e32 v90, 0xbfb8aa3b, v99
	v_min_f32_e32 v90, 0x42a00000, v90
	v_exp_f32_e32 v90, v90
	s_nop 0
	v_add_f32_e32 v90, 1.0, v90
	v_rcp_f32_e32 v90, v90
	s_nop 0
	v_mul_f32_e32 v90, v99, v90
	v_mul_f32_e32 v98, v98, v90
	v_pk_mul_f32 v[90:91], v[94:95], v[158:159] op_sel_hi:[1,0]
	s_nop 0
	v_mul_f32_e32 v94, 0xbfb8aa3b, v91
	v_min_f32_e32 v94, 0x42a00000, v94
	v_exp_f32_e32 v94, v94
	s_nop 0
	v_add_f32_e32 v94, 1.0, v94
	v_rcp_f32_e32 v94, v94
	s_nop 0
	v_mul_f32_e32 v91, v91, v94
	v_mul_f32_e32 v94, v90, v91
	v_mov_b32_e32 v90, v92
	v_mov_b32_e32 v91, v96
	v_pk_mul_f32 v[90:91], v[90:91], v[158:159] op_sel_hi:[1,0]
	v_mov_b32_e32 v96, v93
	v_mul_f32_e32 v92, 0xbfb8aa3b, v91
	v_min_f32_e32 v92, 0x42a00000, v92
	v_exp_f32_e32 v92, v92
	s_nop 0
; __device__ __forceinline__ u32x4 pack8(const f32x4& a, const f32x4& b) { u32x4 w; w.x = cvt_pk_bf16(a[0], a[1]); w.y = cvt_pk_bf16(a[2], a[3]); w.z = cvt_pk_bf16(b[0], b[1]); w.w = cvt_pk_bf16(b[2], b[3]); return w; }
; __device__ __forceinline__ float expneg(float g) { return ex2(fminf(-g * 1.4426950408889634f, 80.f)); }
;     __device__ __forceinline__ void operator()(const f32x4 (&acc)[2][2][4][2], const Unit& u, int wr, int wc, int fr, int fq) const {
;     ...
;         for (int ai = 0; ai < 2; ++ai)
; #pragma unroll
;             for (int m = 0; m < 4; ++m) { f32x4 v[2]; const float rs = rsv[ai][m];
; #pragma unroll
;                 for (int n = 0; n < 2; ++n)
; #pragma unroll
;                     for (int i = 0; i < 4; ++i) { const float g = acc[ai][0][m][n][i] * rs; v[n][i] = g * __builtin_amdgcn_rcpf(1.f + expneg(g)) * (acc[ai][1][m][n][i] * rs); }
;                 *(u32x4*)(act + (size_t)(rowt + ai * HALF + m * 16) * 5632 + col0) = pack8(v[0], v[1]); }
	v_add_f32_e32 v92, 1.0, v92
	v_rcp_f32_e32 v92, v92
	s_nop 0
	v_mul_f32_e32 v91, v91, v92
	v_mul_f32_e32 v92, v90, v91
	v_pk_mul_f32 v[90:91], v[96:97], v[158:159] op_sel_hi:[1,0]
	s_nop 0
	v_mul_f32_e32 v93, 0xbfb8aa3b, v91
	v_min_f32_e32 v93, 0x42a00000, v93
	v_exp_f32_e32 v93, v93
	s_nop 0
	v_add_f32_e32 v93, 1.0, v93
	v_rcp_f32_e32 v93, v93
	s_nop 0
	v_mul_f32_e32 v91, v91, v93
	v_mul_f32_e32 v93, v90, v91
	v_mov_b32_e32 v90, v82
	v_mov_b32_e32 v91, v86
	v_pk_mul_f32 v[90:91], v[90:91], v[158:159] op_sel_hi:[1,0]
	v_mov_b32_e32 v86, v83
	v_mul_f32_e32 v82, 0xbfb8aa3b, v91
	v_min_f32_e32 v82, 0x42a00000, v82
	v_exp_f32_e32 v82, v82
	s_nop 0
	v_add_f32_e32 v82, 1.0, v82
	v_rcp_f32_e32 v82, v82
	s_nop 0
	v_mul_f32_e32 v82, v91, v82
	v_mul_f32_e32 v90, v90, v82
	v_pk_mul_f32 v[82:83], v[86:87], v[158:159] op_sel_hi:[1,0]
	s_nop 0
	v_mul_f32_e32 v86, 0xbfb8aa3b, v83
	v_min_f32_e32 v86, 0x42a00000, v86
	v_exp_f32_e32 v86, v86
	s_nop 0
	v_add_f32_e32 v86, 1.0, v86
	v_rcp_f32_e32 v86, v86
	s_nop 0
	v_mul_f32_e32 v83, v83, v86
	v_mul_f32_e32 v86, v82, v83
	v_mov_b32_e32 v82, v84
	v_mov_b32_e32 v83, v88
	v_pk_mul_f32 v[82:83], v[82:83], v[158:159] op_sel_hi:[1,0]
	v_mov_b32_e32 v88, v85
	v_mul_f32_e32 v84, 0xbfb8aa3b, v83
	v_min_f32_e32 v84, 0x42a00000, v84
	v_exp_f32_e32 v84, v84
	s_nop 0
	v_add_f32_e32 v84, 1.0, v84
	v_rcp_f32_e32 v84, v84
	s_nop 0
	v_mul_f32_e32 v83, v83, v84
	v_mul_f32_e32 v87, v82, v83
	v_pk_mul_f32 v[82:83], v[88:89], v[158:159] op_sel_hi:[1,0]
	s_nop 0
	v_mul_f32_e32 v84, 0xbfb8aa3b, v83
	v_min_f32_e32 v84, 0x42a00000, v84
	v_exp_f32_e32 v84, v84
	s_nop 0
	v_add_f32_e32 v84, 1.0, v84
	v_rcp_f32_e32 v84, v84
	s_nop 0
	v_mul_f32_e32 v83, v83, v84
	v_mul_f32_e32 v85, v82, v83
	v_cvt_pk_bf16_f32 v82, v98, v94
	v_cvt_pk_bf16_f32 v83, v92, v93
	v_cvt_pk_bf16_f32 v84, v90, v86
	v_cvt_pk_bf16_f32 v85, v87, v85
	v_mad_i64_i32 v[86:87], s[2:3], v156, s49, v[114:115]
	v_lshl_add_u64 v[86:87], v[86:87], 0, v[116:117]
	global_store_dwordx4 v[86:87], v[82:85], off
	s_nop 1
	v_mov_b32_e32 v82, v74
	v_mov_b32_e32 v83, v78
	v_pk_mul_f32 v[82:83], v[82:83], v[154:155] op_sel_hi:[1,0]
	v_mov_b32_e32 v78, v75
	v_mul_f32_e32 v74, 0xbfb8aa3b, v83
	v_min_f32_e32 v74, 0x42a00000, v74
	v_exp_f32_e32 v74, v74
	s_nop 0
	v_add_f32_e32 v74, 1.0, v74
	v_rcp_f32_e32 v74, v74
	s_nop 0
	v_mul_f32_e32 v74, v83, v74
	v_mul_f32_e32 v82, v82, v74
	v_pk_mul_f32 v[74:75], v[78:79], v[154:155] op_sel_hi:[1,0]
	s_nop 0
	v_mul_f32_e32 v78, 0xbfb8aa3b, v75
	v_min_f32_e32 v78, 0x42a00000, v78
	v_exp_f32_e32 v78, v78
	s_nop 0
	v_add_f32_e32 v78, 1.0, v78
	v_rcp_f32_e32 v78, v78
	s_nop 0
	v_mul_f32_e32 v75, v75, v78
	v_mul_f32_e32 v78, v74, v75
	v_mov_b32_e32 v74, v76
	v_mov_b32_e32 v75, v80
	v_pk_mul_f32 v[74:75], v[74:75], v[154:155] op_sel_hi:[1,0]
	v_mov_b32_e32 v80, v77
	v_mul_f32_e32 v76, 0xbfb8aa3b, v75
	v_min_f32_e32 v76, 0x42a00000, v76
	v_exp_f32_e32 v76, v76
	s_nop 0
	v_add_f32_e32 v76, 1.0, v76
	v_rcp_f32_e32 v76, v76
	s_nop 0
	v_mul_f32_e32 v75, v75, v76
	v_mul_f32_e32 v76, v74, v75
	v_pk_mul_f32 v[74:75], v[80:81], v[154:155] op_sel_hi:[1,0]
	s_nop 0
	v_mul_f32_e32 v77, 0xbfb8aa3b, v75
	v_min_f32_e32 v77, 0x42a00000, v77
	v_exp_f32_e32 v77, v77
	s_nop 0
	v_add_f32_e32 v77, 1.0, v77
	v_rcp_f32_e32 v77, v77
	s_nop 0
	v_mul_f32_e32 v75, v75, v77
	v_mul_f32_e32 v77, v74, v75
	v_mov_b32_e32 v74, v66
	v_mov_b32_e32 v75, v70
	v_pk_mul_f32 v[74:75], v[74:75], v[154:155] op_sel_hi:[1,0]
	v_mov_b32_e32 v70, v67
	v_mul_f32_e32 v66, 0xbfb8aa3b, v75
	v_min_f32_e32 v66, 0x42a00000, v66
	v_exp_f32_e32 v66, v66
	s_nop 0
	v_add_f32_e32 v66, 1.0, v66
	v_rcp_f32_e32 v66, v66
	s_nop 0
	v_mul_f32_e32 v66, v75, v66
	v_mul_f32_e32 v74, v74, v66
	v_pk_mul_f32 v[66:67], v[70:71], v[154:155] op_sel_hi:[1,0]
	s_nop 0
	v_mul_f32_e32 v70, 0xbfb8aa3b, v67
	v_min_f32_e32 v70, 0x42a00000, v70
	v_exp_f32_e32 v70, v70
	s_nop 0
	v_add_f32_e32 v70, 1.0, v70
	v_rcp_f32_e32 v70, v70
	s_nop 0
	v_mul_f32_e32 v67, v67, v70
	v_mul_f32_e32 v70, v66, v67
	v_mov_b32_e32 v66, v68
	v_mov_b32_e32 v67, v72
	v_pk_mul_f32 v[66:67], v[66:67], v[154:155] op_sel_hi:[1,0]
	v_mov_b32_e32 v72, v69
	v_mul_f32_e32 v68, 0xbfb8aa3b, v67
	v_min_f32_e32 v68, 0x42a00000, v68
	v_exp_f32_e32 v68, v68
	s_nop 0
	v_add_f32_e32 v68, 1.0, v68
	v_rcp_f32_e32 v68, v68
	s_nop 0
	v_mul_f32_e32 v67, v67, v68
	v_mul_f32_e32 v71, v66, v67
	v_pk_mul_f32 v[66:67], v[72:73], v[154:155] op_sel_hi:[1,0]
	s_nop 0
	v_mul_f32_e32 v68, 0xbfb8aa3b, v67
	v_min_f32_e32 v68, 0x42a00000, v68
	v_exp_f32_e32 v68, v68
	s_nop 0
	v_add_f32_e32 v68, 1.0, v68
	v_rcp_f32_e32 v68, v68
	s_nop 0
	v_mul_f32_e32 v67, v67, v68
	v_mul_f32_e32 v69, v66, v67
	v_cvt_pk_bf16_f32 v66, v82, v78
	v_cvt_pk_bf16_f32 v67, v76, v77
	v_cvt_pk_bf16_f32 v68, v74, v70
	v_cvt_pk_bf16_f32 v69, v71, v69
	v_mad_i64_i32 v[70:71], s[2:3], v152, s49, v[114:115]
	v_lshl_add_u64 v[70:71], v[70:71], 0, v[116:117]
	global_store_dwordx4 v[70:71], v[66:69], off
	s_nop 1
	v_mov_b32_e32 v66, v58
	v_mov_b32_e32 v67, v62
	v_pk_mul_f32 v[66:67], v[66:67], v[150:151] op_sel_hi:[1,0]
	v_mov_b32_e32 v62, v59
	v_mul_f32_e32 v58, 0xbfb8aa3b, v67
	v_min_f32_e32 v58, 0x42a00000, v58
	v_exp_f32_e32 v58, v58
	s_nop 0
	v_add_f32_e32 v58, 1.0, v58
	v_rcp_f32_e32 v58, v58
	s_nop 0
	v_mul_f32_e32 v58, v67, v58
	v_mul_f32_e32 v66, v66, v58
	v_pk_mul_f32 v[58:59], v[62:63], v[150:151] op_sel_hi:[1,0]
	s_nop 0
	v_mul_f32_e32 v62, 0xbfb8aa3b, v59
	v_min_f32_e32 v62, 0x42a00000, v62
	v_exp_f32_e32 v62, v62
	s_nop 0
	v_add_f32_e32 v62, 1.0, v62
	v_rcp_f32_e32 v62, v62
	s_nop 0
	v_mul_f32_e32 v59, v59, v62
	v_mul_f32_e32 v62, v58, v59
	v_mov_b32_e32 v58, v60
	v_mov_b32_e32 v59, v64
; __device__ __forceinline__ u32x4 pack8(const f32x4& a, const f32x4& b) { u32x4 w; w.x = cvt_pk_bf16(a[0], a[1]); w.y = cvt_pk_bf16(a[2], a[3]); w.z = cvt_pk_bf16(b[0], b[1]); w.w = cvt_pk_bf16(b[2], b[3]); return w; }
; __device__ __forceinline__ float expneg(float g) { return ex2(fminf(-g * 1.4426950408889634f, 80.f)); }
;     __device__ __forceinline__ void operator()(const f32x4 (&acc)[2][2][4][2], const Unit& u, int wr, int wc, int fr, int fq) const {
;     ...
;         for (int ai = 0; ai < 2; ++ai)
; #pragma unroll
;             for (int m = 0; m < 4; ++m) { f32x4 v[2]; const float rs = rsv[ai][m];
; #pragma unroll
;                 for (int n = 0; n < 2; ++n)
; #pragma unroll
;                     for (int i = 0; i < 4; ++i) { const float g = acc[ai][0][m][n][i] * rs; v[n][i] = g * __builtin_amdgcn_rcpf(1.f + expneg(g)) * (acc[ai][1][m][n][i] * rs); }
;                 *(u32x4*)(act + (size_t)(rowt + ai * HALF + m * 16) * 5632 + col0) = pack8(v[0], v[1]); }
	v_pk_mul_f32 v[58:59], v[58:59], v[150:151] op_sel_hi:[1,0]
	v_mov_b32_e32 v64, v61
	v_mul_f32_e32 v60, 0xbfb8aa3b, v59
	v_min_f32_e32 v60, 0x42a00000, v60
	v_exp_f32_e32 v60, v60
	s_nop 0
	v_add_f32_e32 v60, 1.0, v60
	v_rcp_f32_e32 v60, v60
	s_nop 0
	v_mul_f32_e32 v59, v59, v60
	v_mul_f32_e32 v60, v58, v59
	v_pk_mul_f32 v[58:59], v[64:65], v[150:151] op_sel_hi:[1,0]
	s_nop 0
	v_mul_f32_e32 v61, 0xbfb8aa3b, v59
	v_min_f32_e32 v61, 0x42a00000, v61
	v_exp_f32_e32 v61, v61
	s_nop 0
	v_add_f32_e32 v61, 1.0, v61
	v_rcp_f32_e32 v61, v61
	s_nop 0
	v_mul_f32_e32 v59, v59, v61
	v_mul_f32_e32 v61, v58, v59
	v_mov_b32_e32 v58, v50
	v_mov_b32_e32 v59, v54
	v_pk_mul_f32 v[58:59], v[58:59], v[150:151] op_sel_hi:[1,0]
	v_mov_b32_e32 v54, v51
	v_mul_f32_e32 v50, 0xbfb8aa3b, v59
	v_min_f32_e32 v50, 0x42a00000, v50
	v_exp_f32_e32 v50, v50
	s_nop 0
	v_add_f32_e32 v50, 1.0, v50
	v_rcp_f32_e32 v50, v50
	s_nop 0
	v_mul_f32_e32 v50, v59, v50
	v_mul_f32_e32 v58, v58, v50
	v_pk_mul_f32 v[50:51], v[54:55], v[150:151] op_sel_hi:[1,0]
	s_nop 0
	v_mul_f32_e32 v54, 0xbfb8aa3b, v51
	v_min_f32_e32 v54, 0x42a00000, v54
	v_exp_f32_e32 v54, v54
	s_nop 0
	v_add_f32_e32 v54, 1.0, v54
	v_rcp_f32_e32 v54, v54
	s_nop 0
	v_mul_f32_e32 v51, v51, v54
	v_mul_f32_e32 v54, v50, v51
	v_mov_b32_e32 v50, v52
	v_mov_b32_e32 v51, v56
	v_pk_mul_f32 v[50:51], v[50:51], v[150:151] op_sel_hi:[1,0]
	v_mov_b32_e32 v56, v53
	v_mul_f32_e32 v52, 0xbfb8aa3b, v51
	v_min_f32_e32 v52, 0x42a00000, v52
	v_exp_f32_e32 v52, v52
	s_nop 0
	v_add_f32_e32 v52, 1.0, v52
	v_rcp_f32_e32 v52, v52
	s_nop 0
	v_mul_f32_e32 v51, v51, v52
	v_mul_f32_e32 v55, v50, v51
	v_pk_mul_f32 v[50:51], v[56:57], v[150:151] op_sel_hi:[1,0]
	s_nop 0
	v_mul_f32_e32 v52, 0xbfb8aa3b, v51
	v_min_f32_e32 v52, 0x42a00000, v52
	v_exp_f32_e32 v52, v52
	s_nop 0
	v_add_f32_e32 v52, 1.0, v52
	v_rcp_f32_e32 v52, v52
	s_nop 0
	v_mul_f32_e32 v51, v51, v52
	v_mul_f32_e32 v53, v50, v51
	v_cvt_pk_bf16_f32 v50, v66, v62
	v_cvt_pk_bf16_f32 v51, v60, v61
	v_cvt_pk_bf16_f32 v52, v58, v54
	v_cvt_pk_bf16_f32 v53, v55, v53
	v_mad_i64_i32 v[54:55], s[2:3], v148, s49, v[114:115]
	v_lshl_add_u64 v[54:55], v[54:55], 0, v[116:117]
	global_store_dwordx4 v[54:55], v[50:53], off
	s_nop 1
	v_mov_b32_e32 v50, v42
	v_mov_b32_e32 v51, v46
	v_pk_mul_f32 v[50:51], v[50:51], v[146:147] op_sel_hi:[1,0]
	v_mov_b32_e32 v46, v43
	v_mul_f32_e32 v42, 0xbfb8aa3b, v51
	v_min_f32_e32 v42, 0x42a00000, v42
	v_exp_f32_e32 v42, v42
	s_nop 0
	v_add_f32_e32 v42, 1.0, v42
	v_rcp_f32_e32 v42, v42
	s_nop 0
	v_mul_f32_e32 v42, v51, v42
	v_mul_f32_e32 v50, v50, v42
	v_pk_mul_f32 v[42:43], v[46:47], v[146:147] op_sel_hi:[1,0]
	s_nop 0
	v_mul_f32_e32 v46, 0xbfb8aa3b, v43
	v_min_f32_e32 v46, 0x42a00000, v46
	v_exp_f32_e32 v46, v46
	s_nop 0
	v_add_f32_e32 v46, 1.0, v46
	v_rcp_f32_e32 v46, v46
	s_nop 0
	v_mul_f32_e32 v43, v43, v46
	v_mul_f32_e32 v46, v42, v43
	v_mov_b32_e32 v42, v44
	v_mov_b32_e32 v43, v48
	v_pk_mul_f32 v[42:43], v[42:43], v[146:147] op_sel_hi:[1,0]
	v_mov_b32_e32 v48, v45
	v_mul_f32_e32 v44, 0xbfb8aa3b, v43
	v_min_f32_e32 v44, 0x42a00000, v44
	v_exp_f32_e32 v44, v44
	s_nop 0
	v_add_f32_e32 v44, 1.0, v44
	v_rcp_f32_e32 v44, v44
	s_nop 0
	v_mul_f32_e32 v43, v43, v44
	v_mul_f32_e32 v44, v42, v43
	v_pk_mul_f32 v[42:43], v[48:49], v[146:147] op_sel_hi:[1,0]
	s_nop 0
	v_mul_f32_e32 v45, 0xbfb8aa3b, v43
	v_min_f32_e32 v45, 0x42a00000, v45
	v_exp_f32_e32 v45, v45
	s_nop 0
	v_add_f32_e32 v45, 1.0, v45
	v_rcp_f32_e32 v45, v45
	s_nop 0
	v_mul_f32_e32 v43, v43, v45
	v_mul_f32_e32 v45, v42, v43
	v_mov_b32_e32 v42, v34
	v_mov_b32_e32 v43, v38
	v_pk_mul_f32 v[42:43], v[42:43], v[146:147] op_sel_hi:[1,0]
	v_mov_b32_e32 v38, v35
	v_mul_f32_e32 v34, 0xbfb8aa3b, v43
	v_min_f32_e32 v34, 0x42a00000, v34
	v_exp_f32_e32 v34, v34
	s_nop 0
	v_add_f32_e32 v34, 1.0, v34
	v_rcp_f32_e32 v34, v34
	s_nop 0
	v_mul_f32_e32 v34, v43, v34
	v_mul_f32_e32 v42, v42, v34
	v_pk_mul_f32 v[34:35], v[38:39], v[146:147] op_sel_hi:[1,0]
	s_nop 0
	v_mul_f32_e32 v38, 0xbfb8aa3b, v35
	v_min_f32_e32 v38, 0x42a00000, v38
	v_exp_f32_e32 v38, v38
	s_nop 0
	v_add_f32_e32 v38, 1.0, v38
	v_rcp_f32_e32 v38, v38
	s_nop 0
	v_mul_f32_e32 v35, v35, v38
	v_mul_f32_e32 v38, v34, v35
	v_mov_b32_e32 v34, v36
	v_mov_b32_e32 v35, v40
	v_pk_mul_f32 v[34:35], v[34:35], v[146:147] op_sel_hi:[1,0]
	v_mov_b32_e32 v40, v37
	v_mul_f32_e32 v36, 0xbfb8aa3b, v35
	v_min_f32_e32 v36, 0x42a00000, v36
	v_exp_f32_e32 v36, v36
	s_nop 0
	v_add_f32_e32 v36, 1.0, v36
	v_rcp_f32_e32 v36, v36
	s_nop 0
	v_mul_f32_e32 v35, v35, v36
	v_mul_f32_e32 v39, v34, v35
	v_pk_mul_f32 v[34:35], v[40:41], v[146:147] op_sel_hi:[1,0]
	s_nop 0
	v_mul_f32_e32 v36, 0xbfb8aa3b, v35
	v_min_f32_e32 v36, 0x42a00000, v36
	v_exp_f32_e32 v36, v36
	s_nop 0
	v_add_f32_e32 v36, 1.0, v36
	v_rcp_f32_e32 v36, v36
	s_nop 0
	v_mul_f32_e32 v35, v35, v36
	v_mul_f32_e32 v37, v34, v35
	v_cvt_pk_bf16_f32 v34, v50, v46
	v_cvt_pk_bf16_f32 v35, v44, v45
	v_cvt_pk_bf16_f32 v36, v42, v38
	v_cvt_pk_bf16_f32 v37, v39, v37
	v_mad_i64_i32 v[38:39], s[2:3], v144, s49, v[114:115]
	v_lshl_add_u64 v[38:39], v[38:39], 0, v[116:117]
	global_store_dwordx4 v[38:39], v[34:37], off
	s_nop 1
	v_mov_b32_e32 v34, v26
	v_mov_b32_e32 v35, v30
	v_pk_mul_f32 v[34:35], v[34:35], v[142:143] op_sel_hi:[1,0]
	v_mov_b32_e32 v30, v27
	v_mul_f32_e32 v26, 0xbfb8aa3b, v35
	v_min_f32_e32 v26, 0x42a00000, v26
	v_exp_f32_e32 v26, v26
	s_nop 0
	v_add_f32_e32 v26, 1.0, v26
	v_rcp_f32_e32 v26, v26
	s_nop 0
	v_mul_f32_e32 v26, v35, v26
	v_mul_f32_e32 v34, v34, v26
; __device__ __forceinline__ u32x4 pack8(const f32x4& a, const f32x4& b) { u32x4 w; w.x = cvt_pk_bf16(a[0], a[1]); w.y = cvt_pk_bf16(a[2], a[3]); w.z = cvt_pk_bf16(b[0], b[1]); w.w = cvt_pk_bf16(b[2], b[3]); return w; }
; __device__ __forceinline__ float expneg(float g) { return ex2(fminf(-g * 1.4426950408889634f, 80.f)); }
;     __device__ __forceinline__ void operator()(const f32x4 (&acc)[2][2][4][2], const Unit& u, int wr, int wc, int fr, int fq) const {
;     ...
;         for (int ai = 0; ai < 2; ++ai)
; #pragma unroll
;             for (int m = 0; m < 4; ++m) { f32x4 v[2]; const float rs = rsv[ai][m];
; #pragma unroll
;                 for (int n = 0; n < 2; ++n)
; #pragma unroll
;                     for (int i = 0; i < 4; ++i) { const float g = acc[ai][0][m][n][i] * rs; v[n][i] = g * __builtin_amdgcn_rcpf(1.f + expneg(g)) * (acc[ai][1][m][n][i] * rs); }
;                 *(u32x4*)(act + (size_t)(rowt + ai * HALF + m * 16) * 5632 + col0) = pack8(v[0], v[1]); }
	v_pk_mul_f32 v[26:27], v[30:31], v[142:143] op_sel_hi:[1,0]
	s_nop 0
	v_mul_f32_e32 v30, 0xbfb8aa3b, v27
	v_min_f32_e32 v30, 0x42a00000, v30
	v_exp_f32_e32 v30, v30
	s_nop 0
	v_add_f32_e32 v30, 1.0, v30
	v_rcp_f32_e32 v30, v30
	s_nop 0
	v_mul_f32_e32 v27, v27, v30
	v_mul_f32_e32 v30, v26, v27
	v_mov_b32_e32 v26, v28
	v_mov_b32_e32 v27, v32
	v_pk_mul_f32 v[26:27], v[26:27], v[142:143] op_sel_hi:[1,0]
	v_mov_b32_e32 v32, v29
	v_mul_f32_e32 v28, 0xbfb8aa3b, v27
	v_min_f32_e32 v28, 0x42a00000, v28
	v_exp_f32_e32 v28, v28
	s_nop 0
	v_add_f32_e32 v28, 1.0, v28
	v_rcp_f32_e32 v28, v28
	s_nop 0
	v_mul_f32_e32 v27, v27, v28
	v_mul_f32_e32 v28, v26, v27
	v_pk_mul_f32 v[26:27], v[32:33], v[142:143] op_sel_hi:[1,0]
	s_nop 0
	v_mul_f32_e32 v29, 0xbfb8aa3b, v27
	v_min_f32_e32 v29, 0x42a00000, v29
	v_exp_f32_e32 v29, v29
	s_nop 0
	v_add_f32_e32 v29, 1.0, v29
	v_rcp_f32_e32 v29, v29
	s_nop 0
	v_mul_f32_e32 v27, v27, v29
	v_mul_f32_e32 v29, v26, v27
	v_mov_b32_e32 v26, v18
	v_mov_b32_e32 v27, v22
	v_pk_mul_f32 v[26:27], v[26:27], v[142:143] op_sel_hi:[1,0]
	v_mov_b32_e32 v22, v19
	v_mul_f32_e32 v18, 0xbfb8aa3b, v27
	v_min_f32_e32 v18, 0x42a00000, v18
	v_exp_f32_e32 v18, v18
	s_nop 0
	v_add_f32_e32 v18, 1.0, v18
	v_rcp_f32_e32 v18, v18
	s_nop 0
	v_mul_f32_e32 v18, v27, v18
	v_mul_f32_e32 v26, v26, v18
	v_pk_mul_f32 v[18:19], v[22:23], v[142:143] op_sel_hi:[1,0]
	s_nop 0
	v_mul_f32_e32 v22, 0xbfb8aa3b, v19
	v_min_f32_e32 v22, 0x42a00000, v22
	v_exp_f32_e32 v22, v22
	s_nop 0
	v_add_f32_e32 v22, 1.0, v22
	v_rcp_f32_e32 v22, v22
	s_nop 0
	v_mul_f32_e32 v19, v19, v22
	v_mul_f32_e32 v22, v18, v19
	v_mov_b32_e32 v18, v20
	v_mov_b32_e32 v19, v24
	v_pk_mul_f32 v[18:19], v[18:19], v[142:143] op_sel_hi:[1,0]
	v_mov_b32_e32 v24, v21
	v_mul_f32_e32 v20, 0xbfb8aa3b, v19
	v_min_f32_e32 v20, 0x42a00000, v20
	v_exp_f32_e32 v20, v20
	s_nop 0
	v_add_f32_e32 v20, 1.0, v20
	v_rcp_f32_e32 v20, v20
	s_nop 0
	v_mul_f32_e32 v19, v19, v20
	v_mul_f32_e32 v23, v18, v19
	v_pk_mul_f32 v[18:19], v[24:25], v[142:143] op_sel_hi:[1,0]
	s_nop 0
	v_mul_f32_e32 v20, 0xbfb8aa3b, v19
	v_min_f32_e32 v20, 0x42a00000, v20
	v_exp_f32_e32 v20, v20
	s_nop 0
	v_add_f32_e32 v20, 1.0, v20
	v_rcp_f32_e32 v20, v20
	s_nop 0
	v_mul_f32_e32 v19, v19, v20
	v_mul_f32_e32 v21, v18, v19
	v_cvt_pk_bf16_f32 v18, v34, v30
	v_cvt_pk_bf16_f32 v19, v28, v29
	v_cvt_pk_bf16_f32 v20, v26, v22
	v_cvt_pk_bf16_f32 v21, v23, v21
	v_mad_i64_i32 v[22:23], s[2:3], v140, s49, v[114:115]
	v_lshl_add_u64 v[22:23], v[22:23], 0, v[116:117]
	global_store_dwordx4 v[22:23], v[18:21], off
	s_nop 1
	v_mov_b32_e32 v18, v10
	v_mov_b32_e32 v19, v14
	v_pk_mul_f32 v[18:19], v[18:19], v[130:131] op_sel_hi:[1,0]
	v_mov_b32_e32 v14, v11
	v_mul_f32_e32 v10, 0xbfb8aa3b, v19
	v_min_f32_e32 v10, 0x42a00000, v10
	v_exp_f32_e32 v10, v10
	s_nop 0
	v_add_f32_e32 v10, 1.0, v10
	v_rcp_f32_e32 v10, v10
	s_nop 0
	v_mul_f32_e32 v10, v19, v10
	v_mul_f32_e32 v18, v18, v10
	v_pk_mul_f32 v[10:11], v[14:15], v[130:131] op_sel_hi:[1,0]
	s_nop 0
	v_mul_f32_e32 v14, 0xbfb8aa3b, v11
	v_min_f32_e32 v14, 0x42a00000, v14
	v_exp_f32_e32 v14, v14
	s_nop 0
	v_add_f32_e32 v14, 1.0, v14
	v_rcp_f32_e32 v14, v14
	s_nop 0
	v_mul_f32_e32 v11, v11, v14
	v_mul_f32_e32 v14, v10, v11
	v_mov_b32_e32 v10, v12
	v_mov_b32_e32 v11, v16
	v_pk_mul_f32 v[10:11], v[10:11], v[130:131] op_sel_hi:[1,0]
	v_mov_b32_e32 v16, v13
	v_mul_f32_e32 v12, 0xbfb8aa3b, v11
	v_min_f32_e32 v12, 0x42a00000, v12
	v_exp_f32_e32 v12, v12
	s_nop 0
	v_add_f32_e32 v12, 1.0, v12
	v_rcp_f32_e32 v12, v12
	s_nop 0
	v_mul_f32_e32 v11, v11, v12
	v_mul_f32_e32 v12, v10, v11
	v_pk_mul_f32 v[10:11], v[16:17], v[130:131] op_sel_hi:[1,0]
	s_nop 0
	v_mul_f32_e32 v13, 0xbfb8aa3b, v11
	v_min_f32_e32 v13, 0x42a00000, v13
	v_exp_f32_e32 v13, v13
	s_nop 0
	v_add_f32_e32 v13, 1.0, v13
	v_rcp_f32_e32 v13, v13
	s_nop 0
	v_mul_f32_e32 v11, v11, v13
	v_mul_f32_e32 v13, v10, v11
	v_mov_b32_e32 v10, v2
	v_mov_b32_e32 v11, v6
	v_pk_mul_f32 v[10:11], v[10:11], v[130:131] op_sel_hi:[1,0]
	v_mov_b32_e32 v6, v3
	v_mul_f32_e32 v2, 0xbfb8aa3b, v11
	v_min_f32_e32 v2, 0x42a00000, v2
	v_exp_f32_e32 v2, v2
	s_nop 0
	v_add_f32_e32 v2, 1.0, v2
	v_rcp_f32_e32 v2, v2
	s_nop 0
	v_mul_f32_e32 v2, v11, v2
	v_mul_f32_e32 v10, v10, v2
	v_pk_mul_f32 v[2:3], v[6:7], v[130:131] op_sel_hi:[1,0]
	s_nop 0
	v_mul_f32_e32 v6, 0xbfb8aa3b, v3
	v_min_f32_e32 v6, 0x42a00000, v6
	v_exp_f32_e32 v6, v6
	s_nop 0
	v_add_f32_e32 v6, 1.0, v6
	v_rcp_f32_e32 v6, v6
	s_nop 0
	v_mul_f32_e32 v3, v3, v6
	v_mul_f32_e32 v6, v2, v3
	v_mov_b32_e32 v2, v4
	v_mov_b32_e32 v3, v8
	v_pk_mul_f32 v[2:3], v[2:3], v[130:131] op_sel_hi:[1,0]
	v_mov_b32_e32 v8, v5
	v_mul_f32_e32 v4, 0xbfb8aa3b, v3
	v_min_f32_e32 v4, 0x42a00000, v4
	v_exp_f32_e32 v4, v4
	s_nop 0
	v_add_f32_e32 v4, 1.0, v4
	v_rcp_f32_e32 v4, v4
	s_nop 0
	v_mul_f32_e32 v3, v3, v4
	v_mul_f32_e32 v7, v2, v3
	v_pk_mul_f32 v[2:3], v[8:9], v[130:131] op_sel_hi:[1,0]
	s_nop 0
	v_mul_f32_e32 v4, 0xbfb8aa3b, v3
	v_min_f32_e32 v4, 0x42a00000, v4
	v_exp_f32_e32 v4, v4
	s_nop 0
	v_add_f32_e32 v4, 1.0, v4
	v_rcp_f32_e32 v4, v4
	s_nop 0
	v_mul_f32_e32 v3, v3, v4
	v_mul_f32_e32 v5, v2, v3
	v_cvt_pk_bf16_f32 v2, v18, v14
	v_cvt_pk_bf16_f32 v3, v12, v13
	v_cvt_pk_bf16_f32 v4, v10, v6
	v_cvt_pk_bf16_f32 v5, v7, v5
	v_mad_i64_i32 v[6:7], s[2:3], v138, s49, v[114:115]
	v_lshl_add_u64 v[6:7], v[6:7], 0, v[116:117]
	global_store_dwordx4 v[6:7], v[2:5], off
	s_cbranch_vccnz .LBB0_701
	s_andn2_b64 vcc, exec, s[16:17]
	s_cbranch_vccnz .LBB0_700
	s_barrier
	s_branch .LBB0_700

; __global__ void __launch_bounds__(NWAVES * 64, 2) trunk_fwd(Args args) {
	.amdhsa_kernel _Z9trunk_fwd4Args
		.amdhsa_group_segment_fixed_size 0
		.amdhsa_private_segment_fixed_size 0
		.amdhsa_kernarg_size 496
		.amdhsa_user_sgpr_count 2
		.amdhsa_user_sgpr_dispatch_ptr 0
		.amdhsa_user_sgpr_queue_ptr 0
		.amdhsa_user_sgpr_kernarg_segment_ptr 1
		.amdhsa_user_sgpr_dispatch_id 0
		.amdhsa_user_sgpr_kernarg_preload_length 0
		.amdhsa_user_sgpr_kernarg_preload_offset 0
		.amdhsa_user_sgpr_private_segment_size 0
		.amdhsa_uses_dynamic_stack 0
		.amdhsa_enable_private_segment 0
		.amdhsa_system_sgpr_workgroup_id_x 1
		.amdhsa_system_sgpr_workgroup_id_y 0
		.amdhsa_system_sgpr_workgroup_id_z 0
		.amdhsa_system_sgpr_workgroup_info 0
		.amdhsa_system_vgpr_workitem_id 0
		.amdhsa_next_free_vgpr 255
		.amdhsa_next_free_sgpr 102
		.amdhsa_accum_offset 256
		.amdhsa_reserve_vcc 1
		.amdhsa_float_round_mode_32 0
		.amdhsa_float_round_mode_16_64 0
		.amdhsa_float_denorm_mode_32 3
		.amdhsa_float_denorm_mode_16_64 3
		.amdhsa_dx10_clamp 1
		.amdhsa_ieee_mode 1
		.amdhsa_fp16_overflow 0
		.amdhsa_tg_split 0
		.amdhsa_exception_fp_ieee_invalid_op 0
		.amdhsa_exception_fp_denorm_src 0
		.amdhsa_exception_fp_ieee_div_zero 0
		.amdhsa_exception_fp_ieee_overflow 0
		.amdhsa_exception_fp_ieee_underflow 0
		.amdhsa_exception_fp_ieee_inexact 0
		.amdhsa_exception_int_div_zero 0
	.end_amdhsa_kernel

; __global__ void __launch_bounds__(NWAVES * 64, 2) trunk_fwd(Args args) {
amdhsa.kernels:
  - .agpr_count:     0
    .args:
      - .offset:         0
        .size:           240
        .value_kind:     by_value
      - .offset:         240
        .size:           4
        .value_kind:     hidden_block_count_x
      - .offset:         244
        .size:           4
        .value_kind:     hidden_block_count_y
      - .offset:         248
        .size:           4
        .value_kind:     hidden_block_count_z
      - .offset:         252
        .size:           2
        .value_kind:     hidden_group_size_x
      - .offset:         254
        .size:           2
        .value_kind:     hidden_group_size_y
      - .offset:         256
        .size:           2
        .value_kind:     hidden_group_size_z
      - .offset:         258
        .size:           2
        .value_kind:     hidden_remainder_x
      - .offset:         260
        .size:           2
        .value_kind:     hidden_remainder_y
      - .offset:         262
        .size:           2
        .value_kind:     hidden_remainder_z
      - .offset:         280
        .size:           8
        .value_kind:     hidden_global_offset_x
      - .offset:         288
        .size:           8
        .value_kind:     hidden_global_offset_y
      - .offset:         296
        .size:           8
        .value_kind:     hidden_global_offset_z
      - .offset:         304
        .size:           2
        .value_kind:     hidden_grid_dims
      - .offset:         360
        .size:           4
        .value_kind:     hidden_dynamic_lds_size
    .group_segment_fixed_size: 0
    .kernarg_segment_align: 8
    .kernarg_segment_size: 496
    .language:       OpenCL C
    .language_version:
      - 2
      - 0
    .max_flat_workgroup_size: 512
    .name:           _Z9trunk_fwd4Args
    .private_segment_fixed_size: 0
    .sgpr_count:     108
    .sgpr_spill_count: 236
    .symbol:         _Z9trunk_fwd4Args.kd
    .uniform_work_group_size: 1
    .uses_dynamic_stack: false
    .vgpr_count:     255
    .vgpr_spill_count: 0
    .wavefront_size: 64
